# v47 plus vmcnt/lgkmcnt waits before each GEMM phase barrier merged into one s_waitcnt
# baseline (speedup 1.0000x reference)
; #define PG8_STAGE(bufoff, gbase, voff) do { _Pragma("unroll") for (int _i = 0; _i < 2; ++_i) \
;         __builtin_amdgcn_global_load_lds((const unsigned*)((const char*)(gbase) + (voff)[_i]), (LAS unsigned*)(lds + (bufoff) + ldsw + _i * 8192), 16, 0, 0); } while (0)
; #define PG8_LDA(dst, b, h) do { _Pragma("unroll") for (int m = 0; m < 4; ++m) _Pragma("unroll") for (int k = 0; k < 2; ++k) dst[m][k] = *(const LAS bf16x8*)(lds + PG8_SA(b, h) + aoff + m * 2048 + k * 1024); } while (0)
; #define PG8_LDB(dst, b, h) do { _Pragma("unroll") for (int n = 0; n < 2; ++n) _Pragma("unroll") for (int k = 0; k < 2; ++k) dst[n][k] = *(const LAS bf16x8*)(lds + PG8_SB(b, h) + boff + n * 2048 + k * 1024); } while (0)
; #define PG8_WAIT_V(n) asm volatile("s_waitcnt vmcnt(" #n ")" ::: "memory")
; #define PG8_BAR __builtin_amdgcn_s_barrier()
; template <class Epi, class Sched>
; __device__ __forceinline__ void gemm_phase(LAS unsigned char* lds, const Gemm g, const Sched S, const Epi E, const int tid) {
;     ...
;         for (int t = 0; t < nt; t += 2) {
;             const bool last = (t == nt - 2);
;             const char* a1 = cA + (size_t)(t + 1) * kstep;
;             const char* a2 = last ? nA : cA + (size_t)(t + 2) * kstep; const char* b2 = last ? nB : cB + (size_t)(t + 2) * kstep;
;             const char* a3 = a2 + kstep; const char* b3 = b2 + kstep;
;             PG8_LDB(B0, 0, 0); PG8_LDB(B1, 0, 1); PG8_SCHED; PG8_LDA(At, 0, 0); PG8_STAGE(PG8_SA(1, 1), a1 + hstepA, voffA);
;             PG8_WAIT_V(8); PG8_WAIT_L(0); PG8_BAR; PG8_MMA(0, 0, At, B0); PG8_MMA(0, 1, At, B1); PG8_BAR; PG8_SCHED;
;             PG8_LDA(At, 0, 1); PG8_STAGE(PG8_SB(0, 0), b2, voffB); PG8_STAGE(PG8_SB(0, 1), b2 + hstepB, voffB); PG8_STAGE(PG8_SA(0, 0), a2, voffA);
;             PG8_WAIT_V(8); PG8_WAIT_L(0); PG8_BAR; PG8_MMA(1, 0, At, B0); PG8_MMA(1, 1, At, B1); PG8_BAR; PG8_SCHED;
;             PG8_LDB(B0, 1, 0); PG8_LDB(B1, 1, 1); PG8_SCHED; PG8_LDA(At, 1, 0); PG8_STAGE(PG8_SA(0, 1), a2 + hstepA, voffA);
;             PG8_WAIT_V(8); PG8_WAIT_L(0); PG8_BAR; PG8_MMA(0, 0, At, B0); PG8_MMA(0, 1, At, B1); PG8_BAR; PG8_SCHED;
;             PG8_LDA(At, 1, 1); PG8_STAGE(PG8_SB(1, 0), b3, voffB); PG8_STAGE(PG8_SB(1, 1), b3 + hstepB, voffB); PG8_STAGE(PG8_SA(1, 0), a3, voffA);
;             PG8_WAIT_V(8); PG8_WAIT_L(0); PG8_BAR; PG8_MMA(1, 0, At, B0); PG8_MMA(1, 1, At, B1); PG8_BAR; PG8_SCHED;
.LBB0_299:
	s_add_u32 s10, s22, 0xfffc0080
	s_addc_u32 s11, s23, -1
	s_add_i32 s44, 0, 0x10000
	s_cmp_eq_u32 vcc_hi, 28
	s_cselect_b32 s29, s93, s11
	s_cselect_b32 s28, s94, s10
	v_add_u32_e32 v154, s44, v167
	s_cselect_b32 s27, s95, vcc_lo
	s_cselect_b32 s26, s96, s97
	s_add_i32 s45, 0, 0x14000
	ds_read_b128 v[98:101], v154
	ds_read_b128 v[102:105], v154 offset:1024
	ds_read_b128 v[150:153], v154 offset:2048
	ds_read_b128 v[180:183], v154 offset:3072
	v_add_u32_e32 v154, s45, v167
	ds_read_b128 v[184:187], v154
	ds_read_b128 v[188:191], v154 offset:1024
	ds_read_b128 v[192:195], v154 offset:2048
	ds_read_b128 v[196:199], v154 offset:3072
	v_lshl_add_u64 v[154:155], s[22:23], 0, v[148:149]
	s_add_i32 m0, s47, 0xc000
	ds_read_b128 v[200:203], v179
	ds_read_b128 v[204:207], v179 offset:1024
	ds_read_b128 v[208:211], v179 offset:2048
	ds_read_b128 v[212:215], v179 offset:3072
	ds_read_b128 v[216:219], v179 offset:4096
	ds_read_b128 v[220:223], v179 offset:5120
	ds_read_b128 v[224:227], v179 offset:6144
	ds_read_b128 v[228:231], v179 offset:7168
	global_load_lds_dwordx4 v[154:155], off
	v_lshl_add_u64 v[154:155], s[22:23], 0, v[146:147]
	s_add_i32 m0, s47, 0xe000
	s_nop 0
	global_load_lds_dwordx4 v[154:155], off
	s_waitcnt vmcnt(8) lgkmcnt(0)
	s_setprio 1
	s_barrier
	v_mfma_f32_16x16x32_bf16 v[134:137], v[98:101], v[200:203], v[134:137]
	v_mfma_f32_16x16x32_bf16 v[130:133], v[150:153], v[200:203], v[130:133]
	v_mfma_f32_16x16x32_bf16 v[126:129], v[98:101], v[208:211], v[126:129]
	v_mfma_f32_16x16x32_bf16 v[122:125], v[150:153], v[208:211], v[122:125]
	v_mfma_f32_16x16x32_bf16 v[118:121], v[98:101], v[216:219], v[118:121]
	v_mfma_f32_16x16x32_bf16 v[114:117], v[150:153], v[216:219], v[114:117]
	v_mfma_f32_16x16x32_bf16 v[110:113], v[98:101], v[224:227], v[110:113]
	v_mfma_f32_16x16x32_bf16 v[106:109], v[150:153], v[224:227], v[106:109]
	v_mfma_f32_16x16x32_bf16 v[134:137], v[102:105], v[204:207], v[134:137]
	v_mfma_f32_16x16x32_bf16 v[130:133], v[180:183], v[204:207], v[130:133]
	v_mfma_f32_16x16x32_bf16 v[126:129], v[102:105], v[212:215], v[126:129]
	v_mfma_f32_16x16x32_bf16 v[122:125], v[180:183], v[212:215], v[122:125]
	v_mfma_f32_16x16x32_bf16 v[118:121], v[102:105], v[220:223], v[118:121]
	v_mfma_f32_16x16x32_bf16 v[114:117], v[180:183], v[220:223], v[114:117]
	v_mfma_f32_16x16x32_bf16 v[110:113], v[102:105], v[228:231], v[110:113]
	v_mfma_f32_16x16x32_bf16 v[106:109], v[180:183], v[228:231], v[106:109]
	v_mfma_f32_16x16x32_bf16 v[62:65], v[184:187], v[200:203], v[62:65]
	v_mfma_f32_16x16x32_bf16 v[58:61], v[192:195], v[200:203], v[58:61]
	v_mfma_f32_16x16x32_bf16 v[54:57], v[184:187], v[208:211], v[54:57]
	v_mfma_f32_16x16x32_bf16 v[50:53], v[192:195], v[208:211], v[50:53]
	v_mfma_f32_16x16x32_bf16 v[46:49], v[184:187], v[216:219], v[46:49]
	v_mfma_f32_16x16x32_bf16 v[42:45], v[192:195], v[216:219], v[42:45]
	v_mfma_f32_16x16x32_bf16 v[38:41], v[184:187], v[224:227], v[38:41]
	v_mfma_f32_16x16x32_bf16 v[34:37], v[192:195], v[224:227], v[34:37]
	v_mfma_f32_16x16x32_bf16 v[62:65], v[188:191], v[204:207], v[62:65]
	v_mfma_f32_16x16x32_bf16 v[58:61], v[196:199], v[204:207], v[58:61]
	v_mfma_f32_16x16x32_bf16 v[54:57], v[188:191], v[212:215], v[54:57]
	v_mfma_f32_16x16x32_bf16 v[50:53], v[196:199], v[212:215], v[50:53]
	v_mfma_f32_16x16x32_bf16 v[46:49], v[188:191], v[220:223], v[46:49]
	v_mfma_f32_16x16x32_bf16 v[42:45], v[196:199], v[220:223], v[42:45]
	v_mfma_f32_16x16x32_bf16 v[38:41], v[188:191], v[228:231], v[38:41]
	v_mfma_f32_16x16x32_bf16 v[34:37], v[196:199], v[228:231], v[34:37]
	s_barrier
	s_setprio 0
	s_add_i32 s10, s44, s46
	v_lshl_add_u64 v[154:155], s[26:27], 0, v[142:143]
	s_mov_b32 m0, s10
	ds_read_b128 v[200:203], v179 offset:16384
	ds_read_b128 v[204:207], v179 offset:17408
	ds_read_b128 v[208:211], v179 offset:18432
	ds_read_b128 v[212:215], v179 offset:19456
	ds_read_b128 v[216:219], v179 offset:20480
	ds_read_b128 v[220:223], v179 offset:21504
	ds_read_b128 v[224:227], v179 offset:22528
	ds_read_b128 v[228:231], v179 offset:23552
	global_load_lds_dwordx4 v[154:155], off
	s_add_i32 m0, s10, 0x2000
	s_add_u32 s10, s26, 0x80000
	v_lshl_add_u64 v[232:233], s[26:27], 0, v[138:139]
	s_addc_u32 s11, s27, 0
	s_add_i32 s45, s45, s46
	global_load_lds_dwordx4 v[232:233], off
	v_lshl_add_u64 v[234:235], s[10:11], 0, v[142:143]
	s_mov_b32 m0, s45
	v_lshl_add_u64 v[246:247], s[28:29], 0, v[140:141]
	global_load_lds_dwordx4 v[234:235], off
	v_lshl_add_u64 v[234:235], s[10:11], 0, v[138:139]
	s_add_i32 m0, s45, 0x2000
	s_nop 0
	global_load_lds_dwordx4 v[234:235], off
	v_lshl_add_u64 v[234:235], s[28:29], 0, v[144:145]
	s_mov_b32 m0, s47
	s_nop 0
	global_load_lds_dwordx4 v[234:235], off
	s_mov_b32 m0, s48
	s_nop 0
	global_load_lds_dwordx4 v[246:247], off
	s_waitcnt vmcnt(8) lgkmcnt(0)
	s_setprio 1
	s_barrier
; #define PG8_STAGE(bufoff, gbase, voff) do { _Pragma("unroll") for (int _i = 0; _i < 2; ++_i) \
;         __builtin_amdgcn_global_load_lds((const unsigned*)((const char*)(gbase) + (voff)[_i]), (LAS unsigned*)(lds + (bufoff) + ldsw + _i * 8192), 16, 0, 0); } while (0)
; #define PG8_LDA(dst, b, h) do { _Pragma("unroll") for (int m = 0; m < 4; ++m) _Pragma("unroll") for (int k = 0; k < 2; ++k) dst[m][k] = *(const LAS bf16x8*)(lds + PG8_SA(b, h) + aoff + m * 2048 + k * 1024); } while (0)
; #define PG8_LDB(dst, b, h) do { _Pragma("unroll") for (int n = 0; n < 2; ++n) _Pragma("unroll") for (int k = 0; k < 2; ++k) dst[n][k] = *(const LAS bf16x8*)(lds + PG8_SB(b, h) + boff + n * 2048 + k * 1024); } while (0)
; #define PG8_MMA(ai, bj, At, Bt) do { __builtin_amdgcn_s_setprio(1); _Pragma("unroll") for (int m = 0; m < 4; ++m) _Pragma("unroll") for (int n = 0; n < 2; ++n) _Pragma("unroll") for (int k = 0; k < 2; ++k) \
;         acc[ai][bj][m][n] = __builtin_amdgcn_mfma_f32_16x16x32_bf16(Bt[n][k], At[m][k], acc[ai][bj][m][n], 0, 0, 0); __builtin_amdgcn_s_setprio(0); } while (0)
; #define PG8_WAIT_V(n) asm volatile("s_waitcnt vmcnt(" #n ")" ::: "memory")
; #define PG8_WAIT_L(n) asm volatile("s_waitcnt lgkmcnt(" #n ")" ::: "memory")
; #define PG8_BAR __builtin_amdgcn_s_barrier()
; #define PG8_SCHED __builtin_amdgcn_sched_barrier(0)
; template <class Epi, class Sched>
; __device__ __forceinline__ void gemm_phase(LAS unsigned char* lds, const Gemm g, const Sched S, const Epi E, const int tid) {
;     ...
;             PG8_WAIT_V(8); PG8_WAIT_L(0); PG8_BAR; PG8_MMA(0, 0, At, B0); PG8_MMA(0, 1, At, B1); PG8_BAR; PG8_SCHED;
;             PG8_LDA(At, 0, 1); PG8_STAGE(PG8_SB(0, 0), b2, voffB); PG8_STAGE(PG8_SB(0, 1), b2 + hstepB, voffB); PG8_STAGE(PG8_SA(0, 0), a2, voffA);
;             PG8_WAIT_V(8); PG8_WAIT_L(0); PG8_BAR; PG8_MMA(1, 0, At, B0); PG8_MMA(1, 1, At, B1); PG8_BAR; PG8_SCHED;
;             PG8_LDB(B0, 1, 0); PG8_LDB(B1, 1, 1); PG8_SCHED; PG8_LDA(At, 1, 0); PG8_STAGE(PG8_SA(0, 1), a2 + hstepA, voffA);
;             PG8_WAIT_V(8); PG8_WAIT_L(0); PG8_BAR; PG8_MMA(0, 0, At, B0); PG8_MMA(0, 1, At, B1); PG8_BAR; PG8_SCHED;
	v_mfma_f32_16x16x32_bf16 v[94:97], v[98:101], v[200:203], v[94:97]
	v_mfma_f32_16x16x32_bf16 v[90:93], v[150:153], v[200:203], v[90:93]
	v_mfma_f32_16x16x32_bf16 v[86:89], v[98:101], v[208:211], v[86:89]
	v_mfma_f32_16x16x32_bf16 v[82:85], v[150:153], v[208:211], v[82:85]
	v_mfma_f32_16x16x32_bf16 v[78:81], v[98:101], v[216:219], v[78:81]
	v_mfma_f32_16x16x32_bf16 v[74:77], v[150:153], v[216:219], v[74:77]
	v_mfma_f32_16x16x32_bf16 v[70:73], v[98:101], v[224:227], v[70:73]
	v_mfma_f32_16x16x32_bf16 v[66:69], v[150:153], v[224:227], v[66:69]
	v_mfma_f32_16x16x32_bf16 v[94:97], v[102:105], v[204:207], v[94:97]
	v_mfma_f32_16x16x32_bf16 v[90:93], v[180:183], v[204:207], v[90:93]
	v_mfma_f32_16x16x32_bf16 v[86:89], v[102:105], v[212:215], v[86:89]
	v_mfma_f32_16x16x32_bf16 v[82:85], v[180:183], v[212:215], v[82:85]
	v_mfma_f32_16x16x32_bf16 v[78:81], v[102:105], v[220:223], v[78:81]
	v_mfma_f32_16x16x32_bf16 v[74:77], v[180:183], v[220:223], v[74:77]
	v_mfma_f32_16x16x32_bf16 v[70:73], v[102:105], v[228:231], v[70:73]
	v_mfma_f32_16x16x32_bf16 v[66:69], v[180:183], v[228:231], v[66:69]
	v_mfma_f32_16x16x32_bf16 v[30:33], v[184:187], v[200:203], v[30:33]
	v_mfma_f32_16x16x32_bf16 v[26:29], v[192:195], v[200:203], v[26:29]
	v_mfma_f32_16x16x32_bf16 v[22:25], v[184:187], v[208:211], v[22:25]
	v_mfma_f32_16x16x32_bf16 v[18:21], v[192:195], v[208:211], v[18:21]
	v_mfma_f32_16x16x32_bf16 v[14:17], v[184:187], v[216:219], v[14:17]
	v_mfma_f32_16x16x32_bf16 v[10:13], v[192:195], v[216:219], v[10:13]
	v_mfma_f32_16x16x32_bf16 v[6:9], v[184:187], v[224:227], v[6:9]
	v_mfma_f32_16x16x32_bf16 v[2:5], v[192:195], v[224:227], v[2:5]
	v_mfma_f32_16x16x32_bf16 v[30:33], v[188:191], v[204:207], v[30:33]
	v_mfma_f32_16x16x32_bf16 v[26:29], v[196:199], v[204:207], v[26:29]
	v_mfma_f32_16x16x32_bf16 v[22:25], v[188:191], v[212:215], v[22:25]
	v_mfma_f32_16x16x32_bf16 v[18:21], v[196:199], v[212:215], v[18:21]
	v_mfma_f32_16x16x32_bf16 v[14:17], v[188:191], v[220:223], v[14:17]
	v_mfma_f32_16x16x32_bf16 v[10:13], v[196:199], v[220:223], v[10:13]
	v_mfma_f32_16x16x32_bf16 v[6:9], v[188:191], v[228:231], v[6:9]
	v_mfma_f32_16x16x32_bf16 v[2:5], v[196:199], v[228:231], v[2:5]
	s_barrier
	s_setprio 0
	s_add_i32 s45, 0, 0x18000
	s_add_i32 s6, 0, 0x1c000
	v_add_u32_e32 v180, s45, v167
	v_add_u32_e32 v196, s6, v167
	ds_read_b128 v[98:101], v180
	ds_read_b128 v[102:105], v180 offset:1024
	ds_read_b128 v[150:153], v180 offset:2048
	ds_read_b128 v[180:183], v180 offset:3072
	ds_read_b128 v[184:187], v196
	ds_read_b128 v[188:191], v196 offset:1024
	ds_read_b128 v[192:195], v196 offset:2048
	ds_read_b128 v[196:199], v196 offset:3072
	s_add_u32 s10, s28, 0x40000
	s_addc_u32 s11, s29, 0
	s_mov_b32 m0, s49
	v_lshl_add_u64 v[248:249], s[10:11], 0, v[144:145]
	ds_read_b128 v[200:203], v179 offset:32768
	ds_read_b128 v[204:207], v179 offset:33792
	ds_read_b128 v[208:211], v179 offset:34816
	ds_read_b128 v[212:215], v179 offset:35840
	ds_read_b128 v[216:219], v179 offset:36864
	ds_read_b128 v[220:223], v179 offset:37888
	ds_read_b128 v[224:227], v179 offset:38912
	ds_read_b128 v[228:231], v179 offset:39936
	global_load_lds_dwordx4 v[248:249], off
	v_lshl_add_u64 v[248:249], s[10:11], 0, v[140:141]
	s_mov_b32 m0, s62
	s_nop 0
	global_load_lds_dwordx4 v[248:249], off
	s_waitcnt vmcnt(8) lgkmcnt(0)
	s_setprio 1
	s_barrier
	v_mfma_f32_16x16x32_bf16 v[134:137], v[98:101], v[200:203], v[134:137]
	v_mfma_f32_16x16x32_bf16 v[130:133], v[150:153], v[200:203], v[130:133]
	v_mfma_f32_16x16x32_bf16 v[126:129], v[98:101], v[208:211], v[126:129]
	v_mfma_f32_16x16x32_bf16 v[122:125], v[150:153], v[208:211], v[122:125]
	v_mfma_f32_16x16x32_bf16 v[118:121], v[98:101], v[216:219], v[118:121]
	v_mfma_f32_16x16x32_bf16 v[114:117], v[150:153], v[216:219], v[114:117]
	v_mfma_f32_16x16x32_bf16 v[110:113], v[98:101], v[224:227], v[110:113]
	v_mfma_f32_16x16x32_bf16 v[106:109], v[150:153], v[224:227], v[106:109]
	v_mfma_f32_16x16x32_bf16 v[134:137], v[102:105], v[204:207], v[134:137]
	v_mfma_f32_16x16x32_bf16 v[130:133], v[180:183], v[204:207], v[130:133]
	v_mfma_f32_16x16x32_bf16 v[126:129], v[102:105], v[212:215], v[126:129]
	v_mfma_f32_16x16x32_bf16 v[122:125], v[180:183], v[212:215], v[122:125]
	v_mfma_f32_16x16x32_bf16 v[118:121], v[102:105], v[220:223], v[118:121]
	v_mfma_f32_16x16x32_bf16 v[114:117], v[180:183], v[220:223], v[114:117]
	v_mfma_f32_16x16x32_bf16 v[110:113], v[102:105], v[228:231], v[110:113]
	v_mfma_f32_16x16x32_bf16 v[106:109], v[180:183], v[228:231], v[106:109]
	v_mfma_f32_16x16x32_bf16 v[62:65], v[184:187], v[200:203], v[62:65]
	v_mfma_f32_16x16x32_bf16 v[58:61], v[192:195], v[200:203], v[58:61]
	v_mfma_f32_16x16x32_bf16 v[54:57], v[184:187], v[208:211], v[54:57]
	v_mfma_f32_16x16x32_bf16 v[50:53], v[192:195], v[208:211], v[50:53]
	v_mfma_f32_16x16x32_bf16 v[46:49], v[184:187], v[216:219], v[46:49]
	v_mfma_f32_16x16x32_bf16 v[42:45], v[192:195], v[216:219], v[42:45]
	v_mfma_f32_16x16x32_bf16 v[38:41], v[184:187], v[224:227], v[38:41]
	v_mfma_f32_16x16x32_bf16 v[34:37], v[192:195], v[224:227], v[34:37]
	v_mfma_f32_16x16x32_bf16 v[62:65], v[188:191], v[204:207], v[62:65]
	v_mfma_f32_16x16x32_bf16 v[58:61], v[196:199], v[204:207], v[58:61]
	v_mfma_f32_16x16x32_bf16 v[54:57], v[188:191], v[212:215], v[54:57]
	v_mfma_f32_16x16x32_bf16 v[50:53], v[196:199], v[212:215], v[50:53]
	v_mfma_f32_16x16x32_bf16 v[46:49], v[188:191], v[220:223], v[46:49]
	v_mfma_f32_16x16x32_bf16 v[42:45], v[196:199], v[220:223], v[42:45]
	v_mfma_f32_16x16x32_bf16 v[38:41], v[188:191], v[228:231], v[38:41]
	v_mfma_f32_16x16x32_bf16 v[34:37], v[196:199], v[228:231], v[34:37]
	s_barrier
; #define PG8_STAGE(bufoff, gbase, voff) do { _Pragma("unroll") for (int _i = 0; _i < 2; ++_i) \
;         __builtin_amdgcn_global_load_lds((const unsigned*)((const char*)(gbase) + (voff)[_i]), (LAS unsigned*)(lds + (bufoff) + ldsw + _i * 8192), 16, 0, 0); } while (0)
; #define PG8_LDA(dst, b, h) do { _Pragma("unroll") for (int m = 0; m < 4; ++m) _Pragma("unroll") for (int k = 0; k < 2; ++k) dst[m][k] = *(const LAS bf16x8*)(lds + PG8_SA(b, h) + aoff + m * 2048 + k * 1024); } while (0)
; #define PG8_MMA(ai, bj, At, Bt) do { __builtin_amdgcn_s_setprio(1); _Pragma("unroll") for (int m = 0; m < 4; ++m) _Pragma("unroll") for (int n = 0; n < 2; ++n) _Pragma("unroll") for (int k = 0; k < 2; ++k) \
;         acc[ai][bj][m][n] = __builtin_amdgcn_mfma_f32_16x16x32_bf16(Bt[n][k], At[m][k], acc[ai][bj][m][n], 0, 0, 0); __builtin_amdgcn_s_setprio(0); } while (0)
; #define PG8_WAIT_V(n) asm volatile("s_waitcnt vmcnt(" #n ")" ::: "memory")
; #define PG8_WAIT_L(n) asm volatile("s_waitcnt lgkmcnt(" #n ")" ::: "memory")
; #define PG8_BAR __builtin_amdgcn_s_barrier()
; #define PG8_SCHED __builtin_amdgcn_sched_barrier(0)
; template <class Epi, class Sched>
; __device__ __forceinline__ void gemm_phase(LAS unsigned char* lds, const Gemm g, const Sched S, const Epi E, const int tid) {
;     ...
;             PG8_LDA(At, 1, 1); PG8_STAGE(PG8_SB(1, 0), b3, voffB); PG8_STAGE(PG8_SB(1, 1), b3 + hstepB, voffB); PG8_STAGE(PG8_SA(1, 0), a3, voffA);
;             PG8_WAIT_V(8); PG8_WAIT_L(0); PG8_BAR; PG8_MMA(1, 0, At, B0); PG8_MMA(1, 1, At, B1); PG8_BAR; PG8_SCHED;
;         }
;         if (wr == 0) PG8_BAR;
	s_setprio 0
	s_add_i32 s7, s45, s46
	v_lshl_add_u64 v[154:155], v[154:155], 0, s[64:65]
	s_mov_b32 m0, s7
	ds_read_b128 v[200:203], v179 offset:49152
	ds_read_b128 v[204:207], v179 offset:50176
	ds_read_b128 v[208:211], v179 offset:51200
	ds_read_b128 v[212:215], v179 offset:52224
	ds_read_b128 v[216:219], v179 offset:53248
	ds_read_b128 v[220:223], v179 offset:54272
	ds_read_b128 v[224:227], v179 offset:55296
	ds_read_b128 v[228:231], v179 offset:56320
	global_load_lds_dwordx4 v[154:155], off
	s_add_i32 m0, s7, 0x2000
	s_add_u32 s10, s26, 0x80080
	v_lshl_add_u64 v[154:155], v[232:233], 0, s[64:65]
	s_addc_u32 s11, s27, 0
	s_add_i32 s6, s6, s46
	global_load_lds_dwordx4 v[154:155], off
	v_lshl_add_u64 v[154:155], s[10:11], 0, v[142:143]
	s_mov_b32 m0, s6
	s_nop 0
	global_load_lds_dwordx4 v[154:155], off
	v_lshl_add_u64 v[154:155], s[10:11], 0, v[138:139]
	s_add_i32 m0, s6, 0x2000
	s_nop 0
	global_load_lds_dwordx4 v[154:155], off
	v_lshl_add_u64 v[154:155], v[234:235], 0, s[64:65]
	s_mov_b32 m0, s84
	s_nop 0
	global_load_lds_dwordx4 v[154:155], off
	v_lshl_add_u64 v[154:155], v[246:247], 0, s[64:65]
	s_mov_b32 m0, s85
	s_nop 0
	global_load_lds_dwordx4 v[154:155], off
	s_waitcnt vmcnt(8) lgkmcnt(0)
	s_setprio 1
	s_barrier
	v_mfma_f32_16x16x32_bf16 v[94:97], v[98:101], v[200:203], v[94:97]
	v_mfma_f32_16x16x32_bf16 v[90:93], v[150:153], v[200:203], v[90:93]
	v_mfma_f32_16x16x32_bf16 v[86:89], v[98:101], v[208:211], v[86:89]
	v_mfma_f32_16x16x32_bf16 v[82:85], v[150:153], v[208:211], v[82:85]
	v_mfma_f32_16x16x32_bf16 v[78:81], v[98:101], v[216:219], v[78:81]
	v_mfma_f32_16x16x32_bf16 v[74:77], v[150:153], v[216:219], v[74:77]
	v_mfma_f32_16x16x32_bf16 v[70:73], v[98:101], v[224:227], v[70:73]
	v_mfma_f32_16x16x32_bf16 v[66:69], v[150:153], v[224:227], v[66:69]
	v_mfma_f32_16x16x32_bf16 v[94:97], v[102:105], v[204:207], v[94:97]
	v_mfma_f32_16x16x32_bf16 v[90:93], v[180:183], v[204:207], v[90:93]
	v_mfma_f32_16x16x32_bf16 v[86:89], v[102:105], v[212:215], v[86:89]
	v_mfma_f32_16x16x32_bf16 v[82:85], v[180:183], v[212:215], v[82:85]
	v_mfma_f32_16x16x32_bf16 v[78:81], v[102:105], v[220:223], v[78:81]
	v_mfma_f32_16x16x32_bf16 v[74:77], v[180:183], v[220:223], v[74:77]
	v_mfma_f32_16x16x32_bf16 v[70:73], v[102:105], v[228:231], v[70:73]
	v_mfma_f32_16x16x32_bf16 v[66:69], v[180:183], v[228:231], v[66:69]
	v_mfma_f32_16x16x32_bf16 v[30:33], v[184:187], v[200:203], v[30:33]
	v_mfma_f32_16x16x32_bf16 v[26:29], v[192:195], v[200:203], v[26:29]
	v_mfma_f32_16x16x32_bf16 v[22:25], v[184:187], v[208:211], v[22:25]
	v_mfma_f32_16x16x32_bf16 v[18:21], v[192:195], v[208:211], v[18:21]
	v_mfma_f32_16x16x32_bf16 v[14:17], v[184:187], v[216:219], v[14:17]
	v_mfma_f32_16x16x32_bf16 v[10:13], v[192:195], v[216:219], v[10:13]
	v_mfma_f32_16x16x32_bf16 v[6:9], v[184:187], v[224:227], v[6:9]
	v_mfma_f32_16x16x32_bf16 v[2:5], v[192:195], v[224:227], v[2:5]
	v_mfma_f32_16x16x32_bf16 v[30:33], v[188:191], v[204:207], v[30:33]
	v_mfma_f32_16x16x32_bf16 v[26:29], v[196:199], v[204:207], v[26:29]
	v_mfma_f32_16x16x32_bf16 v[22:25], v[188:191], v[212:215], v[22:25]
	v_mfma_f32_16x16x32_bf16 v[18:21], v[196:199], v[212:215], v[18:21]
	v_mfma_f32_16x16x32_bf16 v[14:17], v[188:191], v[220:223], v[14:17]
	v_mfma_f32_16x16x32_bf16 v[10:13], v[196:199], v[220:223], v[10:13]
	v_mfma_f32_16x16x32_bf16 v[6:9], v[188:191], v[228:231], v[6:9]
	v_mfma_f32_16x16x32_bf16 v[2:5], v[196:199], v[228:231], v[2:5]
	s_barrier
	s_setprio 0
	s_add_i32 vcc_hi, vcc_hi, 2
	s_add_u32 s97, s97, 0x100
	s_addc_u32 vcc_lo, vcc_lo, 0
	s_add_u32 s22, s22, 0x100
	s_addc_u32 s23, s23, 0
	s_cmp_gt_u32 vcc_hi, 29
	s_cbranch_scc0 .LBB0_299
	s_and_b64 vcc, exec, s[18:19]
	s_cbranch_vccz .LBB0_302
	s_barrier

;     __host__ __device__ bool next(int i, Unit& u) const { const int L = i * G + c; if (L >= 32) return false; u.pm = L; u.pn = L >> 4; return true; }
; #define PG8_STAGE(bufoff, gbase, voff) do { _Pragma("unroll") for (int _i = 0; _i < 2; ++_i) \
;         __builtin_amdgcn_global_load_lds((const unsigned*)((const char*)(gbase) + (voff)[_i]), (LAS unsigned*)(lds + (bufoff) + ldsw + _i * 8192), 16, 0, 0); } while (0)
; #define PG8_WAIT_V(n) asm volatile("s_waitcnt vmcnt(" #n ")" ::: "memory")
; #define PG8_WAIT_L(n) asm volatile("s_waitcnt lgkmcnt(" #n ")" ::: "memory")
; #define PG8_BAR __builtin_amdgcn_s_barrier()
; template <class Epi, class Sched>
; __device__ __forceinline__ void gemm_phase(LAS unsigned char* lds, const Gemm g, const Sched S, const Epi E, const int tid) {
;     ...
;         const bool has_next = S.next(ui + 1, nxt);
;         const char* nA = has_next ? (const char*)g.A + (size_t)nxt.pm * tstepA : cA; const char* nB = has_next ? (const char*)g.Bt + (size_t)nxt.pn * tstepB : cB;
;         for (int t = 0; t < nt; t += 2) {
;             const bool last = (t == nt - 2);
;             const char* a1 = cA + (size_t)(t + 1) * kstep;
;             const char* a2 = last ? nA : cA + (size_t)(t + 2) * kstep; const char* b2 = last ? nB : cB + (size_t)(t + 2) * kstep;
;             const char* a3 = a2 + kstep; const char* b3 = b2 + kstep;
;             PG8_LDB(B0, 0, 0); PG8_LDB(B1, 0, 1); PG8_SCHED; PG8_LDA(At, 0, 0); PG8_STAGE(PG8_SA(1, 1), a1 + hstepA, voffA);
;             PG8_WAIT_V(8); PG8_WAIT_L(0); PG8_BAR; PG8_MMA(0, 0, At, B0); PG8_MMA(0, 1, At, B1); PG8_BAR; PG8_SCHED;
;             PG8_LDA(At, 0, 1); PG8_STAGE(PG8_SB(0, 0), b2, voffB); PG8_STAGE(PG8_SB(0, 1), b2 + hstepB, voffB); PG8_STAGE(PG8_SA(0, 0), a2, voffA);
;             PG8_WAIT_V(8); PG8_WAIT_L(0); PG8_BAR; PG8_MMA(1, 0, At, B0); PG8_MMA(1, 1, At, B1); PG8_BAR; PG8_SCHED;
;             PG8_LDB(B0, 1, 0); PG8_LDB(B1, 1, 1); PG8_SCHED; PG8_LDA(At, 1, 0); PG8_STAGE(PG8_SA(0, 1), a2 + hstepA, voffA);
;             PG8_WAIT_V(8); PG8_WAIT_L(0); PG8_BAR; PG8_MMA(0, 0, At, B0); PG8_MMA(0, 1, At, B1); PG8_BAR; PG8_SCHED;
;             PG8_LDA(At, 1, 1); PG8_STAGE(PG8_SB(1, 0), b3, voffB); PG8_STAGE(PG8_SB(1, 1), b3 + hstepB, voffB); PG8_STAGE(PG8_SA(1, 0), a3, voffA);
;             PG8_WAIT_V(8); PG8_WAIT_L(0); PG8_BAR; PG8_MMA(1, 0, At, B0); PG8_MMA(1, 1, At, B1); PG8_BAR; PG8_SCHED;
.LBB0_310:
	s_mov_b32 s6, s92
	s_ashr_i32 s92, s89, 4
	s_cmp_lt_i32 s89, 32
	s_mov_b64 s[42:43], s[4:5]
	s_cselect_b64 s[4:5], -1, 0
	s_and_b64 s[4:5], s[4:5], exec
	s_cselect_b32 s4, s92, s6
	s_ashr_i32 s5, s4, 31
	s_lshl_b64 s[4:5], s[4:5], 17
	s_add_u32 s4, s25, s4
	s_addc_u32 s5, s46, s5
	s_cmp_lt_i32 s89, 32
	s_cselect_b64 s[10:11], -1, 0
	s_and_b64 s[10:11], s[10:11], exec
	s_cselect_b32 s10, s89, s93
	v_add_u32_e32 v130, s44, v70
	s_cselect_b32 s26, s4, s42
	s_cselect_b32 s27, s5, s43
	s_ashr_i32 s11, s10, 31
	ds_read_b128 v[2:5], v130
	ds_read_b128 v[6:9], v130 offset:1024
	ds_read_b128 v[10:13], v130 offset:2048
	ds_read_b128 v[14:17], v130 offset:3072
	s_lshl_b64 s[10:11], s[10:11], 17
	s_mov_b64 s[40:41], s[16:17]
	s_add_u32 s16, s8, s10
	s_addc_u32 s17, s9, s11
	s_cmp_lt_i32 s89, 32
	s_cselect_b64 s[22:23], -1, 0
	s_and_b64 s[10:11], s[22:23], exec
	s_cselect_b32 s29, s17, s41
	s_cselect_b32 s28, s16, s40
	s_add_u32 s10, s40, 0x10080
	s_addc_u32 s11, s41, 0
	s_add_i32 s97, s37, 0xc000
	v_lshl_add_u64 v[50:51], s[10:11], 0, v[68:69]
	s_mov_b32 m0, s97
	s_add_i32 s13, s37, 0xe000
	ds_read_b128 v[18:21], v71
	ds_read_b128 v[22:25], v71 offset:1024
	ds_read_b128 v[26:29], v71 offset:2048
	ds_read_b128 v[30:33], v71 offset:3072
	ds_read_b128 v[34:37], v71 offset:4096
	ds_read_b128 v[38:41], v71 offset:5120
	ds_read_b128 v[42:45], v71 offset:6144
	ds_read_b128 v[46:49], v71 offset:7168
	global_load_lds_dwordx4 v[50:51], off
	v_lshl_add_u64 v[50:51], s[10:11], 0, v[66:67]
	s_mov_b32 m0, s13
	s_nop 0
	global_load_lds_dwordx4 v[50:51], off
	s_waitcnt vmcnt(8) lgkmcnt(0)
	s_setprio 1
	s_barrier
	v_mfma_f32_16x16x32_bf16 v[50:53], v[2:5], v[18:21], 0
	v_mfma_f32_16x16x32_bf16 v[18:21], v[10:13], v[18:21], 0
	v_mfma_f32_16x16x32_bf16 v[50:53], v[6:9], v[22:25], v[50:53]
	v_mfma_f32_16x16x32_bf16 v[18:21], v[14:17], v[22:25], v[18:21]
	v_mfma_f32_16x16x32_bf16 v[22:25], v[2:5], v[26:29], 0
	v_mfma_f32_16x16x32_bf16 v[26:29], v[10:13], v[26:29], 0
	v_mfma_f32_16x16x32_bf16 v[22:25], v[6:9], v[30:33], v[22:25]
	v_mfma_f32_16x16x32_bf16 v[26:29], v[14:17], v[30:33], v[26:29]
	v_mfma_f32_16x16x32_bf16 v[30:33], v[2:5], v[34:37], 0
	v_mfma_f32_16x16x32_bf16 v[34:37], v[10:13], v[34:37], 0
	v_mfma_f32_16x16x32_bf16 v[30:33], v[6:9], v[38:41], v[30:33]
	v_mfma_f32_16x16x32_bf16 v[34:37], v[14:17], v[38:41], v[34:37]
	v_mfma_f32_16x16x32_bf16 v[38:41], v[2:5], v[42:45], 0
	v_mfma_f32_16x16x32_bf16 v[42:45], v[10:13], v[42:45], 0
	v_mfma_f32_16x16x32_bf16 v[38:41], v[6:9], v[46:49], v[38:41]
	v_mfma_f32_16x16x32_bf16 v[42:45], v[14:17], v[46:49], v[42:45]
	s_barrier
	s_setprio 0
	s_add_i32 s96, s44, s47
	v_lshl_add_u64 v[120:121], s[42:43], 0, v[68:69]
	s_mov_b64 s[6:7], 0x100
	s_add_i32 s94, s96, 0x2000
	v_lshl_add_u64 v[88:89], v[120:121], 0, s[6:7]
	s_mov_b32 m0, s96
	v_lshl_add_u64 v[122:123], s[42:43], 0, v[66:67]
	s_add_u32 s10, s42, 0x10100
	ds_read_b128 v[46:49], v71 offset:16384
	ds_read_b128 v[54:57], v71 offset:17408
	ds_read_b128 v[58:61], v71 offset:18432
	ds_read_b128 v[62:65], v71 offset:19456
	ds_read_b128 v[72:75], v71 offset:20480
	ds_read_b128 v[76:79], v71 offset:21504
	ds_read_b128 v[80:83], v71 offset:22528
	ds_read_b128 v[84:87], v71 offset:23552
	global_load_lds_dwordx4 v[88:89], off
	v_lshl_add_u64 v[88:89], v[122:123], 0, s[6:7]
	s_mov_b32 m0, s94
	s_addc_u32 s11, s43, 0
	global_load_lds_dwordx4 v[88:89], off
	v_lshl_add_u64 v[88:89], s[10:11], 0, v[68:69]
	s_mov_b32 m0, s48
	v_lshl_add_u64 v[124:125], s[40:41], 0, v[68:69]
	global_load_lds_dwordx4 v[88:89], off
	v_lshl_add_u64 v[88:89], s[10:11], 0, v[66:67]
	s_mov_b32 m0, s49
	v_lshl_add_u64 v[126:127], s[40:41], 0, v[66:67]
	global_load_lds_dwordx4 v[88:89], off
	v_lshl_add_u64 v[88:89], v[124:125], 0, s[6:7]
	s_mov_b32 m0, s37
	s_nop 0
	global_load_lds_dwordx4 v[88:89], off
	v_lshl_add_u64 v[88:89], v[126:127], 0, s[6:7]
	s_mov_b32 m0, s62
	s_nop 0
	global_load_lds_dwordx4 v[88:89], off
	s_waitcnt vmcnt(8) lgkmcnt(0)
	s_setprio 1
	s_barrier
	v_mfma_f32_16x16x32_bf16 v[88:91], v[2:5], v[46:49], 0
	v_mfma_f32_16x16x32_bf16 v[46:49], v[10:13], v[46:49], 0
	v_mfma_f32_16x16x32_bf16 v[88:91], v[6:9], v[54:57], v[88:91]
	v_mfma_f32_16x16x32_bf16 v[46:49], v[14:17], v[54:57], v[46:49]
	v_mfma_f32_16x16x32_bf16 v[54:57], v[2:5], v[58:61], 0
	v_mfma_f32_16x16x32_bf16 v[58:61], v[10:13], v[58:61], 0
	v_mfma_f32_16x16x32_bf16 v[54:57], v[6:9], v[62:65], v[54:57]
	v_mfma_f32_16x16x32_bf16 v[58:61], v[14:17], v[62:65], v[58:61]
	v_mfma_f32_16x16x32_bf16 v[62:65], v[2:5], v[72:75], 0
	v_mfma_f32_16x16x32_bf16 v[2:5], v[2:5], v[80:83], 0
	v_mfma_f32_16x16x32_bf16 v[62:65], v[6:9], v[76:79], v[62:65]
	v_mfma_f32_16x16x32_bf16 v[2:5], v[6:9], v[84:87], v[2:5]
	v_mfma_f32_16x16x32_bf16 v[6:9], v[10:13], v[80:83], 0
	v_mfma_f32_16x16x32_bf16 v[72:75], v[10:13], v[72:75], 0
	v_mfma_f32_16x16x32_bf16 v[6:9], v[14:17], v[84:87], v[6:9]
	v_mfma_f32_16x16x32_bf16 v[72:75], v[14:17], v[76:79], v[72:75]
	s_barrier
	s_setprio 0
	v_add_u32_e32 v131, s45, v70
	ds_read_b128 v[10:13], v131
	ds_read_b128 v[14:17], v131 offset:1024
	ds_read_b128 v[76:79], v131 offset:2048
	ds_read_b128 v[80:83], v131 offset:3072
	s_add_u32 s10, s40, 0x10100
	s_addc_u32 s11, s41, 0
	s_mov_b32 m0, s68
	v_lshl_add_u64 v[128:129], s[10:11], 0, v[68:69]
	ds_read_b128 v[84:87], v71 offset:32768
	ds_read_b128 v[92:95], v71 offset:33792
	ds_read_b128 v[96:99], v71 offset:34816
	ds_read_b128 v[100:103], v71 offset:35840
	ds_read_b128 v[104:107], v71 offset:36864
	ds_read_b128 v[108:111], v71 offset:37888
	ds_read_b128 v[112:115], v71 offset:38912
	ds_read_b128 v[116:119], v71 offset:39936
	global_load_lds_dwordx4 v[128:129], off
	v_lshl_add_u64 v[128:129], s[10:11], 0, v[66:67]
	s_mov_b32 m0, s69
	s_nop 0
	global_load_lds_dwordx4 v[128:129], off
	s_waitcnt vmcnt(8) lgkmcnt(0)
	s_setprio 1
	s_barrier
; #define PG8_STAGE(bufoff, gbase, voff) do { _Pragma("unroll") for (int _i = 0; _i < 2; ++_i) \
;         __builtin_amdgcn_global_load_lds((const unsigned*)((const char*)(gbase) + (voff)[_i]), (LAS unsigned*)(lds + (bufoff) + ldsw + _i * 8192), 16, 0, 0); } while (0)
; #define PG8_LDA(dst, b, h) do { _Pragma("unroll") for (int m = 0; m < 4; ++m) _Pragma("unroll") for (int k = 0; k < 2; ++k) dst[m][k] = *(const LAS bf16x8*)(lds + PG8_SA(b, h) + aoff + m * 2048 + k * 1024); } while (0)
; #define PG8_LDB(dst, b, h) do { _Pragma("unroll") for (int n = 0; n < 2; ++n) _Pragma("unroll") for (int k = 0; k < 2; ++k) dst[n][k] = *(const LAS bf16x8*)(lds + PG8_SB(b, h) + boff + n * 2048 + k * 1024); } while (0)
; #define PG8_MMA(ai, bj, At, Bt) do { __builtin_amdgcn_s_setprio(1); _Pragma("unroll") for (int m = 0; m < 4; ++m) _Pragma("unroll") for (int n = 0; n < 2; ++n) _Pragma("unroll") for (int k = 0; k < 2; ++k) \
;         acc[ai][bj][m][n] = __builtin_amdgcn_mfma_f32_16x16x32_bf16(Bt[n][k], At[m][k], acc[ai][bj][m][n], 0, 0, 0); __builtin_amdgcn_s_setprio(0); } while (0)
; #define PG8_WAIT_V(n) asm volatile("s_waitcnt vmcnt(" #n ")" ::: "memory")
; #define PG8_WAIT_L(n) asm volatile("s_waitcnt lgkmcnt(" #n ")" ::: "memory")
; #define PG8_BAR __builtin_amdgcn_s_barrier()
; template <class Epi, class Sched>
; __device__ __forceinline__ void gemm_phase(LAS unsigned char* lds, const Gemm g, const Sched S, const Epi E, const int tid) {
;     ...
;             PG8_WAIT_V(8); PG8_WAIT_L(0); PG8_BAR; PG8_MMA(0, 0, At, B0); PG8_MMA(0, 1, At, B1); PG8_BAR; PG8_SCHED;
;             PG8_LDA(At, 0, 1); PG8_STAGE(PG8_SB(0, 0), b2, voffB); PG8_STAGE(PG8_SB(0, 1), b2 + hstepB, voffB); PG8_STAGE(PG8_SA(0, 0), a2, voffA);
;             PG8_WAIT_V(8); PG8_WAIT_L(0); PG8_BAR; PG8_MMA(1, 0, At, B0); PG8_MMA(1, 1, At, B1); PG8_BAR; PG8_SCHED;
;             PG8_LDB(B0, 1, 0); PG8_LDB(B1, 1, 1); PG8_SCHED; PG8_LDA(At, 1, 0); PG8_STAGE(PG8_SA(0, 1), a2 + hstepA, voffA);
;             PG8_WAIT_V(8); PG8_WAIT_L(0); PG8_BAR; PG8_MMA(0, 0, At, B0); PG8_MMA(0, 1, At, B1); PG8_BAR; PG8_SCHED;
;             PG8_LDA(At, 1, 1); PG8_STAGE(PG8_SB(1, 0), b3, voffB); PG8_STAGE(PG8_SB(1, 1), b3 + hstepB, voffB); PG8_STAGE(PG8_SA(1, 0), a3, voffA);
;             PG8_WAIT_V(8); PG8_WAIT_L(0); PG8_BAR; PG8_MMA(1, 0, At, B0); PG8_MMA(1, 1, At, B1); PG8_BAR; PG8_SCHED;
	v_mfma_f32_16x16x32_bf16 v[50:53], v[10:13], v[84:87], v[50:53]
	v_mfma_f32_16x16x32_bf16 v[18:21], v[76:79], v[84:87], v[18:21]
	v_mfma_f32_16x16x32_bf16 v[22:25], v[10:13], v[96:99], v[22:25]
	v_mfma_f32_16x16x32_bf16 v[26:29], v[76:79], v[96:99], v[26:29]
	v_mfma_f32_16x16x32_bf16 v[30:33], v[10:13], v[104:107], v[30:33]
	v_mfma_f32_16x16x32_bf16 v[34:37], v[76:79], v[104:107], v[34:37]
	v_mfma_f32_16x16x32_bf16 v[38:41], v[10:13], v[112:115], v[38:41]
	v_mfma_f32_16x16x32_bf16 v[42:45], v[76:79], v[112:115], v[42:45]
	v_mfma_f32_16x16x32_bf16 v[50:53], v[14:17], v[92:95], v[50:53]
	v_mfma_f32_16x16x32_bf16 v[18:21], v[80:83], v[92:95], v[18:21]
	v_mfma_f32_16x16x32_bf16 v[22:25], v[14:17], v[100:103], v[22:25]
	v_mfma_f32_16x16x32_bf16 v[26:29], v[80:83], v[100:103], v[26:29]
	v_mfma_f32_16x16x32_bf16 v[30:33], v[14:17], v[108:111], v[30:33]
	v_mfma_f32_16x16x32_bf16 v[34:37], v[80:83], v[108:111], v[34:37]
	v_mfma_f32_16x16x32_bf16 v[38:41], v[14:17], v[116:119], v[38:41]
	v_mfma_f32_16x16x32_bf16 v[42:45], v[80:83], v[116:119], v[42:45]
	s_barrier
	s_setprio 0
	s_add_i32 vcc_lo, s45, s47
	s_mov_b64 s[6:7], 0x180
	s_add_i32 s95, vcc_lo, 0x2000
	v_lshl_add_u64 v[120:121], v[120:121], 0, s[6:7]
	s_mov_b32 m0, vcc_lo
	s_add_u32 s10, s42, 0x10180
	ds_read_b128 v[84:87], v71 offset:49152
	ds_read_b128 v[92:95], v71 offset:50176
	ds_read_b128 v[96:99], v71 offset:51200
	ds_read_b128 v[100:103], v71 offset:52224
	ds_read_b128 v[104:107], v71 offset:53248
	ds_read_b128 v[108:111], v71 offset:54272
	ds_read_b128 v[112:115], v71 offset:55296
	ds_read_b128 v[116:119], v71 offset:56320
	global_load_lds_dwordx4 v[120:121], off
	v_lshl_add_u64 v[120:121], v[122:123], 0, s[6:7]
	s_mov_b32 m0, s95
	s_addc_u32 s11, s43, 0
	global_load_lds_dwordx4 v[120:121], off
	v_lshl_add_u64 v[120:121], s[10:11], 0, v[68:69]
	s_mov_b32 m0, s85
	s_nop 0
	global_load_lds_dwordx4 v[120:121], off
	v_lshl_add_u64 v[120:121], s[10:11], 0, v[66:67]
	s_mov_b32 m0, s88
	s_nop 0
	global_load_lds_dwordx4 v[120:121], off
	v_lshl_add_u64 v[120:121], v[124:125], 0, s[6:7]
	s_mov_b32 m0, s83
	s_nop 0
	global_load_lds_dwordx4 v[120:121], off
	v_lshl_add_u64 v[120:121], v[126:127], 0, s[6:7]
	s_mov_b32 m0, s84
	s_nop 0
	global_load_lds_dwordx4 v[120:121], off
	s_waitcnt vmcnt(8) lgkmcnt(0)
	s_setprio 1
	s_barrier
	v_mfma_f32_16x16x32_bf16 v[46:49], v[76:79], v[84:87], v[46:49]
	v_mfma_f32_16x16x32_bf16 v[54:57], v[10:13], v[96:99], v[54:57]
	v_mfma_f32_16x16x32_bf16 v[58:61], v[76:79], v[96:99], v[58:61]
	v_mfma_f32_16x16x32_bf16 v[62:65], v[10:13], v[104:107], v[62:65]
	v_mfma_f32_16x16x32_bf16 v[2:5], v[10:13], v[112:115], v[2:5]
	v_mfma_f32_16x16x32_bf16 v[6:9], v[76:79], v[112:115], v[6:9]
	v_mfma_f32_16x16x32_bf16 v[88:91], v[10:13], v[84:87], v[88:91]
	v_mfma_f32_16x16x32_bf16 v[46:49], v[80:83], v[92:95], v[46:49]
	v_mfma_f32_16x16x32_bf16 v[54:57], v[14:17], v[100:103], v[54:57]
	v_mfma_f32_16x16x32_bf16 v[58:61], v[80:83], v[100:103], v[58:61]
	v_mfma_f32_16x16x32_bf16 v[62:65], v[14:17], v[108:111], v[62:65]
	v_mfma_f32_16x16x32_bf16 v[72:75], v[76:79], v[104:107], v[72:75]
	v_mfma_f32_16x16x32_bf16 v[2:5], v[14:17], v[116:119], v[2:5]
	v_mfma_f32_16x16x32_bf16 v[6:9], v[80:83], v[116:119], v[6:9]
	v_mfma_f32_16x16x32_bf16 v[88:91], v[14:17], v[92:95], v[88:91]
	v_mfma_f32_16x16x32_bf16 v[72:75], v[80:83], v[108:111], v[72:75]
	s_barrier
	s_setprio 0
	ds_read_b128 v[10:13], v130
	ds_read_b128 v[14:17], v130 offset:1024
	ds_read_b128 v[76:79], v130 offset:2048
	ds_read_b128 v[80:83], v130 offset:3072
	s_add_u32 s10, s40, 0x10180
	s_addc_u32 s11, s41, 0
	s_mov_b32 m0, s97
	v_lshl_add_u64 v[120:121], s[10:11], 0, v[68:69]
	ds_read_b128 v[84:87], v71
	ds_read_b128 v[92:95], v71 offset:1024
	ds_read_b128 v[96:99], v71 offset:2048
	ds_read_b128 v[100:103], v71 offset:3072
	ds_read_b128 v[104:107], v71 offset:4096
	ds_read_b128 v[108:111], v71 offset:5120
	ds_read_b128 v[112:115], v71 offset:6144
	ds_read_b128 v[116:119], v71 offset:7168
	global_load_lds_dwordx4 v[120:121], off
	v_lshl_add_u64 v[120:121], s[10:11], 0, v[66:67]
	s_mov_b32 m0, s13
	s_nop 0
	global_load_lds_dwordx4 v[120:121], off
	s_waitcnt vmcnt(8) lgkmcnt(0)
	s_setprio 1
	s_barrier
	v_mfma_f32_16x16x32_bf16 v[38:41], v[10:13], v[112:115], v[38:41]
	v_mfma_f32_16x16x32_bf16 v[50:53], v[10:13], v[84:87], v[50:53]
	v_mfma_f32_16x16x32_bf16 v[18:21], v[76:79], v[84:87], v[18:21]
	v_mfma_f32_16x16x32_bf16 v[22:25], v[10:13], v[96:99], v[22:25]
	v_mfma_f32_16x16x32_bf16 v[26:29], v[76:79], v[96:99], v[26:29]
	v_mfma_f32_16x16x32_bf16 v[30:33], v[10:13], v[104:107], v[30:33]
	v_mfma_f32_16x16x32_bf16 v[34:37], v[76:79], v[104:107], v[34:37]
	v_mfma_f32_16x16x32_bf16 v[84:87], v[14:17], v[116:119], v[38:41]
	v_mfma_f32_16x16x32_bf16 v[38:41], v[76:79], v[112:115], v[42:45]
	v_mfma_f32_16x16x32_bf16 v[50:53], v[14:17], v[92:95], v[50:53]
	v_mfma_f32_16x16x32_bf16 v[18:21], v[80:83], v[92:95], v[18:21]
	v_mfma_f32_16x16x32_bf16 v[22:25], v[14:17], v[100:103], v[22:25]
	v_mfma_f32_16x16x32_bf16 v[26:29], v[80:83], v[100:103], v[26:29]
	v_mfma_f32_16x16x32_bf16 v[30:33], v[14:17], v[108:111], v[30:33]
	v_mfma_f32_16x16x32_bf16 v[34:37], v[80:83], v[108:111], v[34:37]
	v_mfma_f32_16x16x32_bf16 v[42:45], v[80:83], v[116:119], v[38:41]
	s_barrier
; #define PG8_STAGE(bufoff, gbase, voff) do { _Pragma("unroll") for (int _i = 0; _i < 2; ++_i) \
;         __builtin_amdgcn_global_load_lds((const unsigned*)((const char*)(gbase) + (voff)[_i]), (LAS unsigned*)(lds + (bufoff) + ldsw + _i * 8192), 16, 0, 0); } while (0)
; #define PG8_LDA(dst, b, h) do { _Pragma("unroll") for (int m = 0; m < 4; ++m) _Pragma("unroll") for (int k = 0; k < 2; ++k) dst[m][k] = *(const LAS bf16x8*)(lds + PG8_SA(b, h) + aoff + m * 2048 + k * 1024); } while (0)
; #define PG8_LDB(dst, b, h) do { _Pragma("unroll") for (int n = 0; n < 2; ++n) _Pragma("unroll") for (int k = 0; k < 2; ++k) dst[n][k] = *(const LAS bf16x8*)(lds + PG8_SB(b, h) + boff + n * 2048 + k * 1024); } while (0)
; #define PG8_MMA(ai, bj, At, Bt) do { __builtin_amdgcn_s_setprio(1); _Pragma("unroll") for (int m = 0; m < 4; ++m) _Pragma("unroll") for (int n = 0; n < 2; ++n) _Pragma("unroll") for (int k = 0; k < 2; ++k) \
;         acc[ai][bj][m][n] = __builtin_amdgcn_mfma_f32_16x16x32_bf16(Bt[n][k], At[m][k], acc[ai][bj][m][n], 0, 0, 0); __builtin_amdgcn_s_setprio(0); } while (0)
; #define PG8_WAIT_V(n) asm volatile("s_waitcnt vmcnt(" #n ")" ::: "memory")
; #define PG8_WAIT_L(n) asm volatile("s_waitcnt lgkmcnt(" #n ")" ::: "memory")
; #define PG8_BAR __builtin_amdgcn_s_barrier()
; template <class Epi, class Sched>
; __device__ __forceinline__ void gemm_phase(LAS unsigned char* lds, const Gemm g, const Sched S, const Epi E, const int tid) {
;     ...
;             PG8_WAIT_V(8); PG8_WAIT_L(0); PG8_BAR; PG8_MMA(0, 0, At, B0); PG8_MMA(0, 1, At, B1); PG8_BAR; PG8_SCHED;
;             PG8_LDA(At, 0, 1); PG8_STAGE(PG8_SB(0, 0), b2, voffB); PG8_STAGE(PG8_SB(0, 1), b2 + hstepB, voffB); PG8_STAGE(PG8_SA(0, 0), a2, voffA);
;             PG8_WAIT_V(8); PG8_WAIT_L(0); PG8_BAR; PG8_MMA(1, 0, At, B0); PG8_MMA(1, 1, At, B1); PG8_BAR; PG8_SCHED;
;             PG8_LDB(B0, 1, 0); PG8_LDB(B1, 1, 1); PG8_SCHED; PG8_LDA(At, 1, 0); PG8_STAGE(PG8_SA(0, 1), a2 + hstepA, voffA);
;             PG8_WAIT_V(8); PG8_WAIT_L(0); PG8_BAR; PG8_MMA(0, 0, At, B0); PG8_MMA(0, 1, At, B1); PG8_BAR; PG8_SCHED;
;             PG8_LDA(At, 1, 1); PG8_STAGE(PG8_SB(1, 0), b3, voffB); PG8_STAGE(PG8_SB(1, 1), b3 + hstepB, voffB); PG8_STAGE(PG8_SA(1, 0), a3, voffA);
;             PG8_WAIT_V(8); PG8_WAIT_L(0); PG8_BAR; PG8_MMA(1, 0, At, B0); PG8_MMA(1, 1, At, B1); PG8_BAR; PG8_SCHED;
;         }
;         if (wr == 0) PG8_BAR;
	s_setprio 0
	s_mov_b32 m0, s96
	v_lshl_add_u64 v[132:133], s[26:27], 0, v[68:69]
	s_add_u32 s10, s26, 0x10000
	ds_read_b128 v[38:41], v71 offset:16384
	ds_read_b128 v[92:95], v71 offset:17408
	ds_read_b128 v[96:99], v71 offset:18432
	ds_read_b128 v[100:103], v71 offset:19456
	ds_read_b128 v[104:107], v71 offset:20480
	ds_read_b128 v[108:111], v71 offset:21504
	ds_read_b128 v[112:115], v71 offset:22528
	ds_read_b128 v[116:119], v71 offset:23552
	global_load_lds_dwordx4 v[132:133], off
	v_lshl_add_u64 v[134:135], s[26:27], 0, v[66:67]
	s_mov_b32 m0, s94
	s_addc_u32 s11, s27, 0
	global_load_lds_dwordx4 v[134:135], off
	v_lshl_add_u64 v[120:121], s[10:11], 0, v[68:69]
	s_mov_b32 m0, s48
	v_lshl_add_u64 v[136:137], s[28:29], 0, v[68:69]
	global_load_lds_dwordx4 v[120:121], off
	v_lshl_add_u64 v[120:121], s[10:11], 0, v[66:67]
	s_mov_b32 m0, s49
	v_lshl_add_u64 v[138:139], s[28:29], 0, v[66:67]
	global_load_lds_dwordx4 v[120:121], off
	s_mov_b32 m0, s37
	s_nop 0
	global_load_lds_dwordx4 v[136:137], off
	s_mov_b32 m0, s62
	s_nop 0
	global_load_lds_dwordx4 v[138:139], off
	s_waitcnt vmcnt(8) lgkmcnt(0)
	s_setprio 1
	s_barrier
	v_mfma_f32_16x16x32_bf16 v[88:91], v[10:13], v[38:41], v[88:91]
	v_mfma_f32_16x16x32_bf16 v[38:41], v[76:79], v[38:41], v[46:49]
	v_mfma_f32_16x16x32_bf16 v[88:91], v[14:17], v[92:95], v[88:91]
	v_mfma_f32_16x16x32_bf16 v[92:95], v[80:83], v[92:95], v[38:41]
	v_mfma_f32_16x16x32_bf16 v[38:41], v[10:13], v[96:99], v[54:57]
	v_mfma_f32_16x16x32_bf16 v[120:123], v[14:17], v[100:103], v[38:41]
	v_mfma_f32_16x16x32_bf16 v[38:41], v[76:79], v[96:99], v[58:61]
	v_mfma_f32_16x16x32_bf16 v[96:99], v[80:83], v[100:103], v[38:41]
	v_mfma_f32_16x16x32_bf16 v[38:41], v[10:13], v[104:107], v[62:65]
	v_mfma_f32_16x16x32_bf16 v[2:5], v[10:13], v[112:115], v[2:5]
	v_mfma_f32_16x16x32_bf16 v[100:103], v[14:17], v[108:111], v[38:41]
	v_mfma_f32_16x16x32_bf16 v[38:41], v[76:79], v[104:107], v[72:75]
	v_mfma_f32_16x16x32_bf16 v[2:5], v[14:17], v[116:119], v[2:5]
	v_mfma_f32_16x16x32_bf16 v[6:9], v[76:79], v[112:115], v[6:9]
	v_mfma_f32_16x16x32_bf16 v[72:75], v[80:83], v[108:111], v[38:41]
	v_mfma_f32_16x16x32_bf16 v[76:79], v[80:83], v[116:119], v[6:9]
	s_barrier
	s_setprio 0
	s_nop 1
	ds_read_b128 v[6:9], v131
	ds_read_b128 v[80:83], v131 offset:1024
	ds_read_b128 v[104:107], v131 offset:2048
	ds_read_b128 v[108:111], v131 offset:3072
	s_add_u32 s10, s28, 0x10000
	s_addc_u32 s11, s29, 0
	s_mov_b32 m0, s68
	v_lshl_add_u64 v[54:55], s[10:11], 0, v[68:69]
	ds_read_b128 v[10:13], v71 offset:32768
	ds_read_b128 v[14:17], v71 offset:33792
	ds_read_b128 v[38:41], v71 offset:34816
	ds_read_b128 v[46:49], v71 offset:35840
	ds_read_b128 v[112:115], v71 offset:36864
	ds_read_b128 v[116:119], v71 offset:37888
	ds_read_b128 v[124:127], v71 offset:38912
	ds_read_b128 v[128:131], v71 offset:39936
	global_load_lds_dwordx4 v[54:55], off
	v_lshl_add_u64 v[54:55], s[10:11], 0, v[66:67]
	s_mov_b32 m0, s69
	s_nop 0
	global_load_lds_dwordx4 v[54:55], off
	s_waitcnt vmcnt(8) lgkmcnt(0)
	s_setprio 1
	s_barrier
	v_mfma_f32_16x16x32_bf16 v[50:53], v[6:9], v[10:13], v[50:53]
	v_mfma_f32_16x16x32_bf16 v[10:13], v[104:107], v[10:13], v[18:21]
	v_mfma_f32_16x16x32_bf16 v[58:61], v[108:111], v[14:17], v[10:13]
	v_mfma_f32_16x16x32_bf16 v[10:13], v[6:9], v[38:41], v[22:25]
	v_mfma_f32_16x16x32_bf16 v[54:57], v[80:83], v[46:49], v[10:13]
	v_mfma_f32_16x16x32_bf16 v[10:13], v[104:107], v[38:41], v[26:29]
	v_mfma_f32_16x16x32_bf16 v[62:65], v[80:83], v[14:17], v[50:53]
	v_mfma_f32_16x16x32_bf16 v[50:53], v[108:111], v[46:49], v[10:13]
	v_mfma_f32_16x16x32_bf16 v[10:13], v[6:9], v[112:115], v[30:33]
	v_mfma_f32_16x16x32_bf16 v[46:49], v[80:83], v[116:119], v[10:13]
	v_mfma_f32_16x16x32_bf16 v[10:13], v[104:107], v[112:115], v[34:37]
	v_mfma_f32_16x16x32_bf16 v[38:41], v[108:111], v[116:119], v[10:13]
	v_mfma_f32_16x16x32_bf16 v[10:13], v[6:9], v[124:127], v[84:87]
	v_mfma_f32_16x16x32_bf16 v[30:33], v[80:83], v[128:131], v[10:13]
	v_mfma_f32_16x16x32_bf16 v[10:13], v[104:107], v[124:127], v[42:45]
	v_mfma_f32_16x16x32_bf16 v[22:25], v[108:111], v[128:131], v[10:13]
	s_barrier
	s_setprio 0
	s_mov_b32 m0, vcc_lo
	v_lshl_add_u64 v[26:27], v[132:133], 0, s[64:65]
	s_add_u32 s10, s26, 0x10080
	ds_read_b128 v[10:13], v71 offset:49152
	ds_read_b128 v[14:17], v71 offset:50176
	ds_read_b128 v[18:21], v71 offset:51200
	ds_read_b128 v[84:87], v71 offset:52224
	ds_read_b128 v[112:115], v71 offset:53248
	ds_read_b128 v[116:119], v71 offset:54272
	ds_read_b128 v[124:127], v71 offset:55296
	ds_read_b128 v[128:131], v71 offset:56320
	global_load_lds_dwordx4 v[26:27], off
	v_lshl_add_u64 v[26:27], v[134:135], 0, s[64:65]
	s_mov_b32 m0, s95
	s_addc_u32 s11, s27, 0
	global_load_lds_dwordx4 v[26:27], off
	v_lshl_add_u64 v[26:27], s[10:11], 0, v[68:69]
	s_mov_b32 m0, s85
	s_nop 0
	global_load_lds_dwordx4 v[26:27], off
	v_lshl_add_u64 v[26:27], s[10:11], 0, v[66:67]
	s_mov_b32 m0, s88
	s_nop 0
	global_load_lds_dwordx4 v[26:27], off
	v_lshl_add_u64 v[26:27], v[136:137], 0, s[64:65]
	s_mov_b32 m0, s83
	s_nop 0
	global_load_lds_dwordx4 v[26:27], off
	v_lshl_add_u64 v[26:27], v[138:139], 0, s[64:65]
	s_mov_b32 m0, s84
	s_nop 0
	global_load_lds_dwordx4 v[26:27], off
	s_waitcnt vmcnt(8) lgkmcnt(0)
	s_setprio 1
	s_barrier
	v_mfma_f32_16x16x32_bf16 v[26:29], v[6:9], v[10:13], v[88:91]
	v_mfma_f32_16x16x32_bf16 v[10:13], v[104:107], v[10:13], v[92:95]
	v_mfma_f32_16x16x32_bf16 v[34:37], v[108:111], v[14:17], v[10:13]
	v_mfma_f32_16x16x32_bf16 v[10:13], v[6:9], v[18:21], v[120:123]
	v_mfma_f32_16x16x32_bf16 v[42:45], v[80:83], v[14:17], v[26:29]
	v_mfma_f32_16x16x32_bf16 v[26:29], v[80:83], v[84:87], v[10:13]
	v_mfma_f32_16x16x32_bf16 v[10:13], v[104:107], v[18:21], v[96:99]
	v_mfma_f32_16x16x32_bf16 v[18:21], v[108:111], v[84:87], v[10:13]
	v_mfma_f32_16x16x32_bf16 v[10:13], v[6:9], v[112:115], v[100:103]
	v_mfma_f32_16x16x32_bf16 v[2:5], v[6:9], v[124:127], v[2:5]
	v_mfma_f32_16x16x32_bf16 v[14:17], v[80:83], v[116:119], v[10:13]
	v_mfma_f32_16x16x32_bf16 v[10:13], v[104:107], v[112:115], v[72:75]
	v_mfma_f32_16x16x32_bf16 v[6:9], v[80:83], v[128:131], v[2:5]
	v_mfma_f32_16x16x32_bf16 v[2:5], v[104:107], v[124:127], v[76:79]
	v_mfma_f32_16x16x32_bf16 v[10:13], v[108:111], v[116:119], v[10:13]
	v_mfma_f32_16x16x32_bf16 v[2:5], v[108:111], v[128:131], v[2:5]
	s_barrier
	s_setprio 0
	s_andn2_b64 vcc, exec, s[18:19]
	s_cbranch_vccnz .LBB0_312
	s_barrier

; #define PG8_STAGE(bufoff, gbase, voff) do { _Pragma("unroll") for (int _i = 0; _i < 2; ++_i) \
;         __builtin_amdgcn_global_load_lds((const unsigned*)((const char*)(gbase) + (voff)[_i]), (LAS unsigned*)(lds + (bufoff) + ldsw + _i * 8192), 16, 0, 0); } while (0)
; #define PG8_LDA(dst, b, h) do { _Pragma("unroll") for (int m = 0; m < 4; ++m) _Pragma("unroll") for (int k = 0; k < 2; ++k) dst[m][k] = *(const LAS bf16x8*)(lds + PG8_SA(b, h) + aoff + m * 2048 + k * 1024); } while (0)
; #define PG8_LDB(dst, b, h) do { _Pragma("unroll") for (int n = 0; n < 2; ++n) _Pragma("unroll") for (int k = 0; k < 2; ++k) dst[n][k] = *(const LAS bf16x8*)(lds + PG8_SB(b, h) + boff + n * 2048 + k * 1024); } while (0)
; #define PG8_WAIT_V(n) asm volatile("s_waitcnt vmcnt(" #n ")" ::: "memory")
; #define PG8_BAR __builtin_amdgcn_s_barrier()
; template <class Epi, class Sched>
; __device__ __forceinline__ void gemm_phase(LAS unsigned char* lds, const Gemm g, const Sched S, const Epi E, const int tid) {
;     ...
;         for (int t = 0; t < nt; t += 2) {
;             const bool last = (t == nt - 2);
;             const char* a1 = cA + (size_t)(t + 1) * kstep;
;             const char* a2 = last ? nA : cA + (size_t)(t + 2) * kstep; const char* b2 = last ? nB : cB + (size_t)(t + 2) * kstep;
;             const char* a3 = a2 + kstep; const char* b3 = b2 + kstep;
;             PG8_LDB(B0, 0, 0); PG8_LDB(B1, 0, 1); PG8_SCHED; PG8_LDA(At, 0, 0); PG8_STAGE(PG8_SA(1, 1), a1 + hstepA, voffA);
;             PG8_WAIT_V(8); PG8_WAIT_L(0); PG8_BAR; PG8_MMA(0, 0, At, B0); PG8_MMA(0, 1, At, B1); PG8_BAR; PG8_SCHED;
;             PG8_LDA(At, 0, 1); PG8_STAGE(PG8_SB(0, 0), b2, voffB); PG8_STAGE(PG8_SB(0, 1), b2 + hstepB, voffB); PG8_STAGE(PG8_SA(0, 0), a2, voffA);
;             PG8_WAIT_V(8); PG8_WAIT_L(0); PG8_BAR; PG8_MMA(1, 0, At, B0); PG8_MMA(1, 1, At, B1); PG8_BAR; PG8_SCHED;
;             PG8_LDB(B0, 1, 0); PG8_LDB(B1, 1, 1); PG8_SCHED; PG8_LDA(At, 1, 0); PG8_STAGE(PG8_SA(0, 1), a2 + hstepA, voffA);
;             PG8_WAIT_V(8); PG8_WAIT_L(0); PG8_BAR; PG8_MMA(0, 0, At, B0); PG8_MMA(0, 1, At, B1); PG8_BAR; PG8_SCHED;
;             PG8_LDA(At, 1, 1); PG8_STAGE(PG8_SB(1, 0), b3, voffB); PG8_STAGE(PG8_SB(1, 1), b3 + hstepB, voffB); PG8_STAGE(PG8_SA(1, 0), a3, voffA);
;             PG8_WAIT_V(8); PG8_WAIT_L(0); PG8_BAR; PG8_MMA(1, 0, At, B0); PG8_MMA(1, 1, At, B1); PG8_BAR; PG8_SCHED;
.LBB0_332:
	s_add_u32 s10, s44, 0xfffc0080
	s_addc_u32 s11, s45, -1
	s_add_i32 vcc_lo, 0, 0x10000
	s_cmp_eq_u32 s97, 12
	s_cselect_b32 s83, s7, s11
	s_cselect_b32 s82, s92, s10
	v_add_u32_e32 v154, vcc_lo, v157
	s_cselect_b32 s47, s93, s96
	s_cselect_b32 s46, s94, s95
	s_add_i32 vcc_hi, 0, 0x14000
	s_waitcnt lgkmcnt(0)
	ds_read_b128 v[130:133], v154
	ds_read_b128 v[134:137], v154 offset:1024
	ds_read_b128 v[150:153], v154 offset:2048
	ds_read_b128 v[160:163], v154 offset:3072
	v_add_u32_e32 v154, vcc_hi, v157
	ds_read_b128 v[164:167], v154
	ds_read_b128 v[180:183], v154 offset:1024
	ds_read_b128 v[184:187], v154 offset:2048
	ds_read_b128 v[188:191], v154 offset:3072
	v_lshl_add_u64 v[154:155], s[44:45], 0, v[148:149]
	s_add_i32 m0, s48, 0xc000
	ds_read_b128 v[192:195], v158
	ds_read_b128 v[196:199], v158 offset:1024
	ds_read_b128 v[200:203], v158 offset:2048
	ds_read_b128 v[204:207], v158 offset:3072
	ds_read_b128 v[208:211], v158 offset:4096
	ds_read_b128 v[212:215], v158 offset:5120
	ds_read_b128 v[216:219], v158 offset:6144
	ds_read_b128 v[220:223], v158 offset:7168
	global_load_lds_dwordx4 v[154:155], off
	v_lshl_add_u64 v[154:155], s[44:45], 0, v[146:147]
	s_add_i32 m0, s48, 0xe000
	s_nop 0
	global_load_lds_dwordx4 v[154:155], off
	s_waitcnt vmcnt(8) lgkmcnt(0)
	s_setprio 1
	s_barrier
	v_mfma_f32_16x16x32_bf16 v[122:125], v[130:133], v[192:195], v[122:125]
	v_mfma_f32_16x16x32_bf16 v[114:117], v[150:153], v[192:195], v[114:117]
	v_mfma_f32_16x16x32_bf16 v[106:109], v[130:133], v[200:203], v[106:109]
	v_mfma_f32_16x16x32_bf16 v[98:101], v[150:153], v[200:203], v[98:101]
	v_mfma_f32_16x16x32_bf16 v[90:93], v[130:133], v[208:211], v[90:93]
	v_mfma_f32_16x16x32_bf16 v[82:85], v[150:153], v[208:211], v[82:85]
	v_mfma_f32_16x16x32_bf16 v[74:77], v[130:133], v[216:219], v[74:77]
	v_mfma_f32_16x16x32_bf16 v[66:69], v[150:153], v[216:219], v[66:69]
	v_mfma_f32_16x16x32_bf16 v[122:125], v[134:137], v[196:199], v[122:125]
	v_mfma_f32_16x16x32_bf16 v[114:117], v[160:163], v[196:199], v[114:117]
	v_mfma_f32_16x16x32_bf16 v[106:109], v[134:137], v[204:207], v[106:109]
	v_mfma_f32_16x16x32_bf16 v[98:101], v[160:163], v[204:207], v[98:101]
	v_mfma_f32_16x16x32_bf16 v[90:93], v[134:137], v[212:215], v[90:93]
	v_mfma_f32_16x16x32_bf16 v[82:85], v[160:163], v[212:215], v[82:85]
	v_mfma_f32_16x16x32_bf16 v[74:77], v[134:137], v[220:223], v[74:77]
	v_mfma_f32_16x16x32_bf16 v[66:69], v[160:163], v[220:223], v[66:69]
	v_mfma_f32_16x16x32_bf16 v[126:129], v[164:167], v[192:195], v[126:129]
	v_mfma_f32_16x16x32_bf16 v[118:121], v[184:187], v[192:195], v[118:121]
	v_mfma_f32_16x16x32_bf16 v[110:113], v[164:167], v[200:203], v[110:113]
	v_mfma_f32_16x16x32_bf16 v[102:105], v[184:187], v[200:203], v[102:105]
	v_mfma_f32_16x16x32_bf16 v[94:97], v[164:167], v[208:211], v[94:97]
	v_mfma_f32_16x16x32_bf16 v[86:89], v[184:187], v[208:211], v[86:89]
	v_mfma_f32_16x16x32_bf16 v[78:81], v[164:167], v[216:219], v[78:81]
	v_mfma_f32_16x16x32_bf16 v[70:73], v[184:187], v[216:219], v[70:73]
	v_mfma_f32_16x16x32_bf16 v[126:129], v[180:183], v[196:199], v[126:129]
	v_mfma_f32_16x16x32_bf16 v[118:121], v[188:191], v[196:199], v[118:121]
	v_mfma_f32_16x16x32_bf16 v[110:113], v[180:183], v[204:207], v[110:113]
	v_mfma_f32_16x16x32_bf16 v[102:105], v[188:191], v[204:207], v[102:105]
	v_mfma_f32_16x16x32_bf16 v[94:97], v[180:183], v[212:215], v[94:97]
	v_mfma_f32_16x16x32_bf16 v[86:89], v[188:191], v[212:215], v[86:89]
	v_mfma_f32_16x16x32_bf16 v[78:81], v[180:183], v[220:223], v[78:81]
	v_mfma_f32_16x16x32_bf16 v[70:73], v[188:191], v[220:223], v[70:73]
	s_barrier
	s_setprio 0
	s_add_i32 s10, vcc_lo, s37
	v_lshl_add_u64 v[154:155], s[46:47], 0, v[140:141]
	s_mov_b32 m0, s10
	ds_read_b128 v[192:195], v158 offset:16384
	ds_read_b128 v[196:199], v158 offset:17408
	ds_read_b128 v[200:203], v158 offset:18432
	ds_read_b128 v[204:207], v158 offset:19456
	ds_read_b128 v[208:211], v158 offset:20480
	ds_read_b128 v[212:215], v158 offset:21504
	ds_read_b128 v[216:219], v158 offset:22528
	ds_read_b128 v[220:223], v158 offset:23552
	global_load_lds_dwordx4 v[154:155], off
	s_add_i32 m0, s10, 0x2000
	s_add_u32 s10, s46, 0x40000
	v_lshl_add_u64 v[224:225], s[46:47], 0, v[144:145]
	s_addc_u32 s11, s47, 0
	s_add_i32 vcc_lo, vcc_hi, s37
	global_load_lds_dwordx4 v[224:225], off
	v_lshl_add_u64 v[226:227], s[10:11], 0, v[140:141]
	s_mov_b32 m0, vcc_lo
	v_lshl_add_u64 v[228:229], s[82:83], 0, v[142:143]
	global_load_lds_dwordx4 v[226:227], off
	v_lshl_add_u64 v[226:227], s[10:11], 0, v[144:145]
	s_add_i32 m0, vcc_lo, 0x2000
	s_nop 0
	global_load_lds_dwordx4 v[226:227], off
	v_lshl_add_u64 v[226:227], s[82:83], 0, v[138:139]
	s_mov_b32 m0, s48
	s_nop 0
	global_load_lds_dwordx4 v[226:227], off
	s_mov_b32 m0, s49
	s_nop 0
	global_load_lds_dwordx4 v[228:229], off
	s_waitcnt vmcnt(8) lgkmcnt(0)
	s_setprio 1
	s_barrier
; #define PG8_STAGE(bufoff, gbase, voff) do { _Pragma("unroll") for (int _i = 0; _i < 2; ++_i) \
;         __builtin_amdgcn_global_load_lds((const unsigned*)((const char*)(gbase) + (voff)[_i]), (LAS unsigned*)(lds + (bufoff) + ldsw + _i * 8192), 16, 0, 0); } while (0)
; #define PG8_LDA(dst, b, h) do { _Pragma("unroll") for (int m = 0; m < 4; ++m) _Pragma("unroll") for (int k = 0; k < 2; ++k) dst[m][k] = *(const LAS bf16x8*)(lds + PG8_SA(b, h) + aoff + m * 2048 + k * 1024); } while (0)
; #define PG8_LDB(dst, b, h) do { _Pragma("unroll") for (int n = 0; n < 2; ++n) _Pragma("unroll") for (int k = 0; k < 2; ++k) dst[n][k] = *(const LAS bf16x8*)(lds + PG8_SB(b, h) + boff + n * 2048 + k * 1024); } while (0)
; #define PG8_MMA(ai, bj, At, Bt) do { __builtin_amdgcn_s_setprio(1); _Pragma("unroll") for (int m = 0; m < 4; ++m) _Pragma("unroll") for (int n = 0; n < 2; ++n) _Pragma("unroll") for (int k = 0; k < 2; ++k) \
;         acc[ai][bj][m][n] = __builtin_amdgcn_mfma_f32_16x16x32_bf16(Bt[n][k], At[m][k], acc[ai][bj][m][n], 0, 0, 0); __builtin_amdgcn_s_setprio(0); } while (0)
; #define PG8_WAIT_V(n) asm volatile("s_waitcnt vmcnt(" #n ")" ::: "memory")
; #define PG8_WAIT_L(n) asm volatile("s_waitcnt lgkmcnt(" #n ")" ::: "memory")
; #define PG8_BAR __builtin_amdgcn_s_barrier()
; #define PG8_SCHED __builtin_amdgcn_sched_barrier(0)
; template <class Epi, class Sched>
; __device__ __forceinline__ void gemm_phase(LAS unsigned char* lds, const Gemm g, const Sched S, const Epi E, const int tid) {
;     ...
;             PG8_WAIT_V(8); PG8_WAIT_L(0); PG8_BAR; PG8_MMA(0, 0, At, B0); PG8_MMA(0, 1, At, B1); PG8_BAR; PG8_SCHED;
;             PG8_LDA(At, 0, 1); PG8_STAGE(PG8_SB(0, 0), b2, voffB); PG8_STAGE(PG8_SB(0, 1), b2 + hstepB, voffB); PG8_STAGE(PG8_SA(0, 0), a2, voffA);
;             PG8_WAIT_V(8); PG8_WAIT_L(0); PG8_BAR; PG8_MMA(1, 0, At, B0); PG8_MMA(1, 1, At, B1); PG8_BAR; PG8_SCHED;
;             PG8_LDB(B0, 1, 0); PG8_LDB(B1, 1, 1); PG8_SCHED; PG8_LDA(At, 1, 0); PG8_STAGE(PG8_SA(0, 1), a2 + hstepA, voffA);
;             PG8_WAIT_V(8); PG8_WAIT_L(0); PG8_BAR; PG8_MMA(0, 0, At, B0); PG8_MMA(0, 1, At, B1); PG8_BAR; PG8_SCHED;
	v_mfma_f32_16x16x32_bf16 v[58:61], v[130:133], v[192:195], v[58:61]
	v_mfma_f32_16x16x32_bf16 v[50:53], v[150:153], v[192:195], v[50:53]
	v_mfma_f32_16x16x32_bf16 v[42:45], v[130:133], v[200:203], v[42:45]
	v_mfma_f32_16x16x32_bf16 v[34:37], v[150:153], v[200:203], v[34:37]
	v_mfma_f32_16x16x32_bf16 v[26:29], v[130:133], v[208:211], v[26:29]
	v_mfma_f32_16x16x32_bf16 v[18:21], v[150:153], v[208:211], v[18:21]
	v_mfma_f32_16x16x32_bf16 v[10:13], v[130:133], v[216:219], v[10:13]
	v_mfma_f32_16x16x32_bf16 v[6:9], v[150:153], v[216:219], v[6:9]
	v_mfma_f32_16x16x32_bf16 v[58:61], v[134:137], v[196:199], v[58:61]
	v_mfma_f32_16x16x32_bf16 v[50:53], v[160:163], v[196:199], v[50:53]
	v_mfma_f32_16x16x32_bf16 v[42:45], v[134:137], v[204:207], v[42:45]
	v_mfma_f32_16x16x32_bf16 v[34:37], v[160:163], v[204:207], v[34:37]
	v_mfma_f32_16x16x32_bf16 v[26:29], v[134:137], v[212:215], v[26:29]
	v_mfma_f32_16x16x32_bf16 v[18:21], v[160:163], v[212:215], v[18:21]
	v_mfma_f32_16x16x32_bf16 v[10:13], v[134:137], v[220:223], v[10:13]
	v_mfma_f32_16x16x32_bf16 v[6:9], v[160:163], v[220:223], v[6:9]
	v_mfma_f32_16x16x32_bf16 v[62:65], v[164:167], v[192:195], v[62:65]
	v_mfma_f32_16x16x32_bf16 v[54:57], v[184:187], v[192:195], v[54:57]
	v_mfma_f32_16x16x32_bf16 v[46:49], v[164:167], v[200:203], v[46:49]
	v_mfma_f32_16x16x32_bf16 v[38:41], v[184:187], v[200:203], v[38:41]
	v_mfma_f32_16x16x32_bf16 v[30:33], v[164:167], v[208:211], v[30:33]
	v_mfma_f32_16x16x32_bf16 v[22:25], v[184:187], v[208:211], v[22:25]
	v_mfma_f32_16x16x32_bf16 v[14:17], v[164:167], v[216:219], v[14:17]
	v_mfma_f32_16x16x32_bf16 v[2:5], v[184:187], v[216:219], v[2:5]
	v_mfma_f32_16x16x32_bf16 v[62:65], v[180:183], v[196:199], v[62:65]
	v_mfma_f32_16x16x32_bf16 v[54:57], v[188:191], v[196:199], v[54:57]
	v_mfma_f32_16x16x32_bf16 v[46:49], v[180:183], v[204:207], v[46:49]
	v_mfma_f32_16x16x32_bf16 v[38:41], v[188:191], v[204:207], v[38:41]
	v_mfma_f32_16x16x32_bf16 v[30:33], v[180:183], v[212:215], v[30:33]
	v_mfma_f32_16x16x32_bf16 v[22:25], v[188:191], v[212:215], v[22:25]
	v_mfma_f32_16x16x32_bf16 v[14:17], v[180:183], v[220:223], v[14:17]
	v_mfma_f32_16x16x32_bf16 v[2:5], v[188:191], v[220:223], v[2:5]
	s_barrier
	s_setprio 0
	s_add_i32 vcc_lo, 0, 0x18000
	v_add_u32_e32 v159, vcc_lo, v157
	s_add_i32 vcc_hi, 0, 0x1c000
	ds_read_b128 v[130:133], v159
	ds_read_b128 v[134:137], v159 offset:1024
	ds_read_b128 v[150:153], v159 offset:2048
	ds_read_b128 v[160:163], v159 offset:3072
	v_add_u32_e32 v159, vcc_hi, v157
	ds_read_b128 v[164:167], v159
	ds_read_b128 v[180:183], v159 offset:1024
	ds_read_b128 v[184:187], v159 offset:2048
	ds_read_b128 v[188:191], v159 offset:3072
	s_add_u32 s10, s82, 0x40000
	s_addc_u32 s11, s83, 0
	s_mov_b32 m0, s62
	v_lshl_add_u64 v[230:231], s[10:11], 0, v[138:139]
	ds_read_b128 v[192:195], v158 offset:32768
	ds_read_b128 v[196:199], v158 offset:33792
	ds_read_b128 v[200:203], v158 offset:34816
	ds_read_b128 v[204:207], v158 offset:35840
	ds_read_b128 v[208:211], v158 offset:36864
	ds_read_b128 v[212:215], v158 offset:37888
	ds_read_b128 v[216:219], v158 offset:38912
	ds_read_b128 v[220:223], v158 offset:39936
	global_load_lds_dwordx4 v[230:231], off
	v_lshl_add_u64 v[230:231], s[10:11], 0, v[142:143]
	s_mov_b32 m0, s68
	s_nop 0
	global_load_lds_dwordx4 v[230:231], off
	s_waitcnt vmcnt(8) lgkmcnt(0)
	s_setprio 1
	s_barrier
	v_mfma_f32_16x16x32_bf16 v[122:125], v[130:133], v[192:195], v[122:125]
	v_mfma_f32_16x16x32_bf16 v[114:117], v[150:153], v[192:195], v[114:117]
	v_mfma_f32_16x16x32_bf16 v[106:109], v[130:133], v[200:203], v[106:109]
	v_mfma_f32_16x16x32_bf16 v[98:101], v[150:153], v[200:203], v[98:101]
	v_mfma_f32_16x16x32_bf16 v[90:93], v[130:133], v[208:211], v[90:93]
	v_mfma_f32_16x16x32_bf16 v[82:85], v[150:153], v[208:211], v[82:85]
	v_mfma_f32_16x16x32_bf16 v[74:77], v[130:133], v[216:219], v[74:77]
	v_mfma_f32_16x16x32_bf16 v[66:69], v[150:153], v[216:219], v[66:69]
	v_mfma_f32_16x16x32_bf16 v[122:125], v[134:137], v[196:199], v[122:125]
	v_mfma_f32_16x16x32_bf16 v[114:117], v[160:163], v[196:199], v[114:117]
	v_mfma_f32_16x16x32_bf16 v[106:109], v[134:137], v[204:207], v[106:109]
	v_mfma_f32_16x16x32_bf16 v[98:101], v[160:163], v[204:207], v[98:101]
	v_mfma_f32_16x16x32_bf16 v[90:93], v[134:137], v[212:215], v[90:93]
	v_mfma_f32_16x16x32_bf16 v[82:85], v[160:163], v[212:215], v[82:85]
	v_mfma_f32_16x16x32_bf16 v[74:77], v[134:137], v[220:223], v[74:77]
	v_mfma_f32_16x16x32_bf16 v[66:69], v[160:163], v[220:223], v[66:69]
	v_mfma_f32_16x16x32_bf16 v[126:129], v[164:167], v[192:195], v[126:129]
	v_mfma_f32_16x16x32_bf16 v[118:121], v[184:187], v[192:195], v[118:121]
	v_mfma_f32_16x16x32_bf16 v[110:113], v[164:167], v[200:203], v[110:113]
	v_mfma_f32_16x16x32_bf16 v[102:105], v[184:187], v[200:203], v[102:105]
	v_mfma_f32_16x16x32_bf16 v[94:97], v[164:167], v[208:211], v[94:97]
	v_mfma_f32_16x16x32_bf16 v[86:89], v[184:187], v[208:211], v[86:89]
	v_mfma_f32_16x16x32_bf16 v[78:81], v[164:167], v[216:219], v[78:81]
	v_mfma_f32_16x16x32_bf16 v[70:73], v[184:187], v[216:219], v[70:73]
	v_mfma_f32_16x16x32_bf16 v[126:129], v[180:183], v[196:199], v[126:129]
	v_mfma_f32_16x16x32_bf16 v[118:121], v[188:191], v[196:199], v[118:121]
	v_mfma_f32_16x16x32_bf16 v[110:113], v[180:183], v[204:207], v[110:113]
	v_mfma_f32_16x16x32_bf16 v[102:105], v[188:191], v[204:207], v[102:105]
	v_mfma_f32_16x16x32_bf16 v[94:97], v[180:183], v[212:215], v[94:97]
	v_mfma_f32_16x16x32_bf16 v[86:89], v[188:191], v[212:215], v[86:89]
	v_mfma_f32_16x16x32_bf16 v[78:81], v[180:183], v[220:223], v[78:81]
	v_mfma_f32_16x16x32_bf16 v[70:73], v[188:191], v[220:223], v[70:73]
	s_barrier
; #define PG8_STAGE(bufoff, gbase, voff) do { _Pragma("unroll") for (int _i = 0; _i < 2; ++_i) \
;         __builtin_amdgcn_global_load_lds((const unsigned*)((const char*)(gbase) + (voff)[_i]), (LAS unsigned*)(lds + (bufoff) + ldsw + _i * 8192), 16, 0, 0); } while (0)
; #define PG8_LDA(dst, b, h) do { _Pragma("unroll") for (int m = 0; m < 4; ++m) _Pragma("unroll") for (int k = 0; k < 2; ++k) dst[m][k] = *(const LAS bf16x8*)(lds + PG8_SA(b, h) + aoff + m * 2048 + k * 1024); } while (0)
; #define PG8_MMA(ai, bj, At, Bt) do { __builtin_amdgcn_s_setprio(1); _Pragma("unroll") for (int m = 0; m < 4; ++m) _Pragma("unroll") for (int n = 0; n < 2; ++n) _Pragma("unroll") for (int k = 0; k < 2; ++k) \
;         acc[ai][bj][m][n] = __builtin_amdgcn_mfma_f32_16x16x32_bf16(Bt[n][k], At[m][k], acc[ai][bj][m][n], 0, 0, 0); __builtin_amdgcn_s_setprio(0); } while (0)
; #define PG8_WAIT_V(n) asm volatile("s_waitcnt vmcnt(" #n ")" ::: "memory")
; #define PG8_WAIT_L(n) asm volatile("s_waitcnt lgkmcnt(" #n ")" ::: "memory")
; #define PG8_BAR __builtin_amdgcn_s_barrier()
; #define PG8_SCHED __builtin_amdgcn_sched_barrier(0)
; template <class Epi, class Sched>
; __device__ __forceinline__ void gemm_phase(LAS unsigned char* lds, const Gemm g, const Sched S, const Epi E, const int tid) {
;     ...
;             PG8_LDA(At, 1, 1); PG8_STAGE(PG8_SB(1, 0), b3, voffB); PG8_STAGE(PG8_SB(1, 1), b3 + hstepB, voffB); PG8_STAGE(PG8_SA(1, 0), a3, voffA);
;             PG8_WAIT_V(8); PG8_WAIT_L(0); PG8_BAR; PG8_MMA(1, 0, At, B0); PG8_MMA(1, 1, At, B1); PG8_BAR; PG8_SCHED;
;         }
;         if (wr == 0) PG8_BAR;
	s_setprio 0
	s_add_i32 s10, vcc_lo, s37
	v_lshl_add_u64 v[154:155], v[154:155], 0, s[64:65]
	s_mov_b32 m0, s10
	ds_read_b128 v[192:195], v158 offset:49152
	ds_read_b128 v[196:199], v158 offset:50176
	ds_read_b128 v[200:203], v158 offset:51200
	ds_read_b128 v[204:207], v158 offset:52224
	ds_read_b128 v[208:211], v158 offset:53248
	ds_read_b128 v[212:215], v158 offset:54272
	ds_read_b128 v[216:219], v158 offset:55296
	ds_read_b128 v[220:223], v158 offset:56320
	global_load_lds_dwordx4 v[154:155], off
	s_add_i32 m0, s10, 0x2000
	s_add_u32 s10, s46, 0x40080
	v_lshl_add_u64 v[154:155], v[224:225], 0, s[64:65]
	s_addc_u32 s11, s47, 0
	s_add_i32 s46, vcc_hi, s37
	global_load_lds_dwordx4 v[154:155], off
	v_lshl_add_u64 v[154:155], s[10:11], 0, v[140:141]
	s_mov_b32 m0, s46
	s_nop 0
	global_load_lds_dwordx4 v[154:155], off
	v_lshl_add_u64 v[154:155], s[10:11], 0, v[144:145]
	s_add_i32 m0, s46, 0x2000
	s_nop 0
	global_load_lds_dwordx4 v[154:155], off
	v_lshl_add_u64 v[154:155], v[226:227], 0, s[64:65]
	s_mov_b32 m0, s88
	s_nop 0
	global_load_lds_dwordx4 v[154:155], off
	v_lshl_add_u64 v[154:155], v[228:229], 0, s[64:65]
	s_mov_b32 m0, s89
	s_nop 0
	global_load_lds_dwordx4 v[154:155], off
	s_waitcnt vmcnt(8) lgkmcnt(0)
	s_setprio 1
	s_barrier
	v_mfma_f32_16x16x32_bf16 v[58:61], v[130:133], v[192:195], v[58:61]
	v_mfma_f32_16x16x32_bf16 v[50:53], v[150:153], v[192:195], v[50:53]
	v_mfma_f32_16x16x32_bf16 v[42:45], v[130:133], v[200:203], v[42:45]
	v_mfma_f32_16x16x32_bf16 v[34:37], v[150:153], v[200:203], v[34:37]
	v_mfma_f32_16x16x32_bf16 v[26:29], v[130:133], v[208:211], v[26:29]
	v_mfma_f32_16x16x32_bf16 v[18:21], v[150:153], v[208:211], v[18:21]
	v_mfma_f32_16x16x32_bf16 v[10:13], v[130:133], v[216:219], v[10:13]
	v_mfma_f32_16x16x32_bf16 v[6:9], v[150:153], v[216:219], v[6:9]
	v_mfma_f32_16x16x32_bf16 v[58:61], v[134:137], v[196:199], v[58:61]
	v_mfma_f32_16x16x32_bf16 v[50:53], v[160:163], v[196:199], v[50:53]
	v_mfma_f32_16x16x32_bf16 v[42:45], v[134:137], v[204:207], v[42:45]
	v_mfma_f32_16x16x32_bf16 v[34:37], v[160:163], v[204:207], v[34:37]
	v_mfma_f32_16x16x32_bf16 v[26:29], v[134:137], v[212:215], v[26:29]
	v_mfma_f32_16x16x32_bf16 v[18:21], v[160:163], v[212:215], v[18:21]
	v_mfma_f32_16x16x32_bf16 v[10:13], v[134:137], v[220:223], v[10:13]
	v_mfma_f32_16x16x32_bf16 v[6:9], v[160:163], v[220:223], v[6:9]
	v_mfma_f32_16x16x32_bf16 v[62:65], v[164:167], v[192:195], v[62:65]
	v_mfma_f32_16x16x32_bf16 v[54:57], v[184:187], v[192:195], v[54:57]
	v_mfma_f32_16x16x32_bf16 v[46:49], v[164:167], v[200:203], v[46:49]
	v_mfma_f32_16x16x32_bf16 v[38:41], v[184:187], v[200:203], v[38:41]
	v_mfma_f32_16x16x32_bf16 v[30:33], v[164:167], v[208:211], v[30:33]
	v_mfma_f32_16x16x32_bf16 v[22:25], v[184:187], v[208:211], v[22:25]
	v_mfma_f32_16x16x32_bf16 v[14:17], v[164:167], v[216:219], v[14:17]
	v_mfma_f32_16x16x32_bf16 v[2:5], v[184:187], v[216:219], v[2:5]
	v_mfma_f32_16x16x32_bf16 v[62:65], v[180:183], v[196:199], v[62:65]
	v_mfma_f32_16x16x32_bf16 v[54:57], v[188:191], v[196:199], v[54:57]
	v_mfma_f32_16x16x32_bf16 v[46:49], v[180:183], v[204:207], v[46:49]
	v_mfma_f32_16x16x32_bf16 v[38:41], v[188:191], v[204:207], v[38:41]
	v_mfma_f32_16x16x32_bf16 v[30:33], v[180:183], v[212:215], v[30:33]
	v_mfma_f32_16x16x32_bf16 v[22:25], v[188:191], v[212:215], v[22:25]
	v_mfma_f32_16x16x32_bf16 v[14:17], v[180:183], v[220:223], v[14:17]
	v_mfma_f32_16x16x32_bf16 v[2:5], v[188:191], v[220:223], v[2:5]
	s_barrier
	s_setprio 0
	s_add_i32 s97, s97, 2
	s_add_u32 s95, s95, 0x100
	s_addc_u32 s96, s96, 0
	s_add_u32 s44, s44, 0x100
	s_addc_u32 s45, s45, 0
	s_cmp_gt_u32 s97, 13
	s_cbranch_scc0 .LBB0_332
	s_and_b64 vcc, exec, s[14:15]
	s_cbranch_vccz .LBB0_335
	s_barrier

; #define PG8_STAGE(bufoff, gbase, voff) do { _Pragma("unroll") for (int _i = 0; _i < 2; ++_i) \
;         __builtin_amdgcn_global_load_lds((const unsigned*)((const char*)(gbase) + (voff)[_i]), (LAS unsigned*)(lds + (bufoff) + ldsw + _i * 8192), 16, 0, 0); } while (0)
; #define PG8_LDA(dst, b, h) do { _Pragma("unroll") for (int m = 0; m < 4; ++m) _Pragma("unroll") for (int k = 0; k < 2; ++k) dst[m][k] = *(const LAS bf16x8*)(lds + PG8_SA(b, h) + aoff + m * 2048 + k * 1024); } while (0)
; #define PG8_LDB(dst, b, h) do { _Pragma("unroll") for (int n = 0; n < 2; ++n) _Pragma("unroll") for (int k = 0; k < 2; ++k) dst[n][k] = *(const LAS bf16x8*)(lds + PG8_SB(b, h) + boff + n * 2048 + k * 1024); } while (0)
; #define PG8_WAIT_V(n) asm volatile("s_waitcnt vmcnt(" #n ")" ::: "memory")
; #define PG8_BAR __builtin_amdgcn_s_barrier()
; template <class Epi, class Sched>
; __device__ __forceinline__ void gemm_phase(LAS unsigned char* lds, const Gemm g, const Sched S, const Epi E, const int tid) {
;     ...
;         for (int t = 0; t < nt; t += 2) {
;             const bool last = (t == nt - 2);
;             const char* a1 = cA + (size_t)(t + 1) * kstep;
;             const char* a2 = last ? nA : cA + (size_t)(t + 2) * kstep; const char* b2 = last ? nB : cB + (size_t)(t + 2) * kstep;
;             const char* a3 = a2 + kstep; const char* b3 = b2 + kstep;
;             PG8_LDB(B0, 0, 0); PG8_LDB(B1, 0, 1); PG8_SCHED; PG8_LDA(At, 0, 0); PG8_STAGE(PG8_SA(1, 1), a1 + hstepA, voffA);
;             PG8_WAIT_V(8); PG8_WAIT_L(0); PG8_BAR; PG8_MMA(0, 0, At, B0); PG8_MMA(0, 1, At, B1); PG8_BAR; PG8_SCHED;
;             PG8_LDA(At, 0, 1); PG8_STAGE(PG8_SB(0, 0), b2, voffB); PG8_STAGE(PG8_SB(0, 1), b2 + hstepB, voffB); PG8_STAGE(PG8_SA(0, 0), a2, voffA);
;             PG8_WAIT_V(8); PG8_WAIT_L(0); PG8_BAR; PG8_MMA(1, 0, At, B0); PG8_MMA(1, 1, At, B1); PG8_BAR; PG8_SCHED;
;             PG8_LDB(B0, 1, 0); PG8_LDB(B1, 1, 1); PG8_SCHED; PG8_LDA(At, 1, 0); PG8_STAGE(PG8_SA(0, 1), a2 + hstepA, voffA);
;             PG8_WAIT_V(8); PG8_WAIT_L(0); PG8_BAR; PG8_MMA(0, 0, At, B0); PG8_MMA(0, 1, At, B1); PG8_BAR; PG8_SCHED;
;             PG8_LDA(At, 1, 1); PG8_STAGE(PG8_SB(1, 0), b3, voffB); PG8_STAGE(PG8_SB(1, 1), b3 + hstepB, voffB); PG8_STAGE(PG8_SA(1, 0), a3, voffA);
;             PG8_WAIT_V(8); PG8_WAIT_L(0); PG8_BAR; PG8_MMA(1, 0, At, B0); PG8_MMA(1, 1, At, B1); PG8_BAR; PG8_SCHED;
.LBB0_471:
	s_add_u32 s12, s10, 0xfffc0080
	s_addc_u32 s13, s11, -1
	s_add_i32 s83, 0, 0x10000
	s_cmp_eq_u32 s82, 12
	s_cselect_b32 s15, s9, s13
	s_cselect_b32 s14, s45, s12
	s_cselect_b32 s13, s43, s62
	s_cselect_b32 s12, s48, s49
	s_add_i32 vcc_lo, 0, 0x14000
	v_add_u32_e32 v154, s83, v165
	v_add_u32_e32 v162, vcc_lo, v165
	ds_read_b128 v[50:53], v154
	ds_read_b128 v[102:105], v154 offset:1024
	ds_read_b128 v[150:153], v154 offset:2048
	ds_read_b128 v[154:157], v154 offset:3072
	ds_read_b128 v[158:161], v162
	ds_read_b128 v[180:183], v162 offset:1024
	ds_read_b128 v[184:187], v162 offset:2048
	ds_read_b128 v[188:191], v162 offset:3072
	v_lshl_add_u64 v[162:163], s[10:11], 0, v[148:149]
	s_add_i32 m0, s41, 0xc000
	ds_read_b128 v[192:195], v166
	ds_read_b128 v[196:199], v166 offset:1024
	ds_read_b128 v[200:203], v166 offset:2048
	ds_read_b128 v[204:207], v166 offset:3072
	ds_read_b128 v[208:211], v166 offset:4096
	ds_read_b128 v[212:215], v166 offset:5120
	ds_read_b128 v[216:219], v166 offset:6144
	ds_read_b128 v[220:223], v166 offset:7168
	global_load_lds_dwordx4 v[162:163], off
	v_lshl_add_u64 v[162:163], s[10:11], 0, v[146:147]
	s_add_i32 m0, s41, 0xe000
	s_nop 0
	global_load_lds_dwordx4 v[162:163], off
	s_waitcnt vmcnt(8) lgkmcnt(0)
	s_setprio 1
	s_barrier
	v_mfma_f32_16x16x32_bf16 v[130:133], v[50:53], v[192:195], v[130:133]
	v_mfma_f32_16x16x32_bf16 v[126:129], v[150:153], v[192:195], v[126:129]
	v_mfma_f32_16x16x32_bf16 v[114:117], v[50:53], v[200:203], v[114:117]
	v_mfma_f32_16x16x32_bf16 v[110:113], v[150:153], v[200:203], v[110:113]
	v_mfma_f32_16x16x32_bf16 v[94:97], v[50:53], v[208:211], v[94:97]
	v_mfma_f32_16x16x32_bf16 v[90:93], v[150:153], v[208:211], v[90:93]
	v_mfma_f32_16x16x32_bf16 v[78:81], v[50:53], v[216:219], v[78:81]
	v_mfma_f32_16x16x32_bf16 v[74:77], v[150:153], v[216:219], v[74:77]
	v_mfma_f32_16x16x32_bf16 v[130:133], v[102:105], v[196:199], v[130:133]
	v_mfma_f32_16x16x32_bf16 v[126:129], v[154:157], v[196:199], v[126:129]
	v_mfma_f32_16x16x32_bf16 v[114:117], v[102:105], v[204:207], v[114:117]
	v_mfma_f32_16x16x32_bf16 v[110:113], v[154:157], v[204:207], v[110:113]
	v_mfma_f32_16x16x32_bf16 v[94:97], v[102:105], v[212:215], v[94:97]
	v_mfma_f32_16x16x32_bf16 v[90:93], v[154:157], v[212:215], v[90:93]
	v_mfma_f32_16x16x32_bf16 v[78:81], v[102:105], v[220:223], v[78:81]
	v_mfma_f32_16x16x32_bf16 v[74:77], v[154:157], v[220:223], v[74:77]
	v_mfma_f32_16x16x32_bf16 v[134:137], v[158:161], v[192:195], v[134:137]
	v_mfma_f32_16x16x32_bf16 v[122:125], v[184:187], v[192:195], v[122:125]
	v_mfma_f32_16x16x32_bf16 v[118:121], v[158:161], v[200:203], v[118:121]
	v_mfma_f32_16x16x32_bf16 v[106:109], v[184:187], v[200:203], v[106:109]
	v_mfma_f32_16x16x32_bf16 v[98:101], v[158:161], v[208:211], v[98:101]
	v_mfma_f32_16x16x32_bf16 v[86:89], v[184:187], v[208:211], v[86:89]
	v_mfma_f32_16x16x32_bf16 v[82:85], v[158:161], v[216:219], v[82:85]
	v_mfma_f32_16x16x32_bf16 v[70:73], v[184:187], v[216:219], v[70:73]
	v_mfma_f32_16x16x32_bf16 v[134:137], v[180:183], v[196:199], v[134:137]
	v_mfma_f32_16x16x32_bf16 v[122:125], v[188:191], v[196:199], v[122:125]
	v_mfma_f32_16x16x32_bf16 v[118:121], v[180:183], v[204:207], v[118:121]
	v_mfma_f32_16x16x32_bf16 v[106:109], v[188:191], v[204:207], v[106:109]
	v_mfma_f32_16x16x32_bf16 v[98:101], v[180:183], v[212:215], v[98:101]
	v_mfma_f32_16x16x32_bf16 v[86:89], v[188:191], v[212:215], v[86:89]
	v_mfma_f32_16x16x32_bf16 v[82:85], v[180:183], v[220:223], v[82:85]
	v_mfma_f32_16x16x32_bf16 v[70:73], v[188:191], v[220:223], v[70:73]
	s_barrier
	s_setprio 0
	s_add_i32 s83, s83, s37
	v_lshl_add_u64 v[162:163], s[12:13], 0, v[140:141]
	s_mov_b32 m0, s83
	ds_read_b128 v[192:195], v166 offset:16384
	ds_read_b128 v[196:199], v166 offset:17408
	ds_read_b128 v[200:203], v166 offset:18432
	ds_read_b128 v[204:207], v166 offset:19456
	ds_read_b128 v[208:211], v166 offset:20480
	ds_read_b128 v[212:215], v166 offset:21504
	ds_read_b128 v[216:219], v166 offset:22528
	ds_read_b128 v[220:223], v166 offset:23552
	global_load_lds_dwordx4 v[162:163], off
	s_add_i32 m0, s83, 0x2000
	s_add_u32 s84, s12, 0x40000
	v_lshl_add_u64 v[224:225], s[12:13], 0, v[144:145]
	s_addc_u32 s85, s13, 0
	s_add_i32 s83, vcc_lo, s37
	global_load_lds_dwordx4 v[224:225], off
	v_lshl_add_u64 v[226:227], s[84:85], 0, v[140:141]
	s_mov_b32 m0, s83
	v_lshl_add_u64 v[228:229], s[14:15], 0, v[142:143]
	global_load_lds_dwordx4 v[226:227], off
	v_lshl_add_u64 v[226:227], s[84:85], 0, v[144:145]
	s_add_i32 m0, s83, 0x2000
	s_nop 0
	global_load_lds_dwordx4 v[226:227], off
	v_lshl_add_u64 v[226:227], s[14:15], 0, v[138:139]
	s_mov_b32 m0, s41
	s_nop 0
	global_load_lds_dwordx4 v[226:227], off
	s_mov_b32 m0, s90
	s_nop 0
	global_load_lds_dwordx4 v[228:229], off
	s_waitcnt vmcnt(8) lgkmcnt(0)
	s_setprio 1
	s_barrier
; #define PG8_STAGE(bufoff, gbase, voff) do { _Pragma("unroll") for (int _i = 0; _i < 2; ++_i) \
;         __builtin_amdgcn_global_load_lds((const unsigned*)((const char*)(gbase) + (voff)[_i]), (LAS unsigned*)(lds + (bufoff) + ldsw + _i * 8192), 16, 0, 0); } while (0)
; #define PG8_LDA(dst, b, h) do { _Pragma("unroll") for (int m = 0; m < 4; ++m) _Pragma("unroll") for (int k = 0; k < 2; ++k) dst[m][k] = *(const LAS bf16x8*)(lds + PG8_SA(b, h) + aoff + m * 2048 + k * 1024); } while (0)
; #define PG8_LDB(dst, b, h) do { _Pragma("unroll") for (int n = 0; n < 2; ++n) _Pragma("unroll") for (int k = 0; k < 2; ++k) dst[n][k] = *(const LAS bf16x8*)(lds + PG8_SB(b, h) + boff + n * 2048 + k * 1024); } while (0)
; #define PG8_MMA(ai, bj, At, Bt) do { __builtin_amdgcn_s_setprio(1); _Pragma("unroll") for (int m = 0; m < 4; ++m) _Pragma("unroll") for (int n = 0; n < 2; ++n) _Pragma("unroll") for (int k = 0; k < 2; ++k) \
;         acc[ai][bj][m][n] = __builtin_amdgcn_mfma_f32_16x16x32_bf16(Bt[n][k], At[m][k], acc[ai][bj][m][n], 0, 0, 0); __builtin_amdgcn_s_setprio(0); } while (0)
; #define PG8_WAIT_V(n) asm volatile("s_waitcnt vmcnt(" #n ")" ::: "memory")
; #define PG8_WAIT_L(n) asm volatile("s_waitcnt lgkmcnt(" #n ")" ::: "memory")
; #define PG8_BAR __builtin_amdgcn_s_barrier()
; #define PG8_SCHED __builtin_amdgcn_sched_barrier(0)
; template <class Epi, class Sched>
; __device__ __forceinline__ void gemm_phase(LAS unsigned char* lds, const Gemm g, const Sched S, const Epi E, const int tid) {
;     ...
;             PG8_WAIT_V(8); PG8_WAIT_L(0); PG8_BAR; PG8_MMA(0, 0, At, B0); PG8_MMA(0, 1, At, B1); PG8_BAR; PG8_SCHED;
;             PG8_LDA(At, 0, 1); PG8_STAGE(PG8_SB(0, 0), b2, voffB); PG8_STAGE(PG8_SB(0, 1), b2 + hstepB, voffB); PG8_STAGE(PG8_SA(0, 0), a2, voffA);
;             PG8_WAIT_V(8); PG8_WAIT_L(0); PG8_BAR; PG8_MMA(1, 0, At, B0); PG8_MMA(1, 1, At, B1); PG8_BAR; PG8_SCHED;
;             PG8_LDB(B0, 1, 0); PG8_LDB(B1, 1, 1); PG8_SCHED; PG8_LDA(At, 1, 0); PG8_STAGE(PG8_SA(0, 1), a2 + hstepA, voffA);
;             PG8_WAIT_V(8); PG8_WAIT_L(0); PG8_BAR; PG8_MMA(0, 0, At, B0); PG8_MMA(0, 1, At, B1); PG8_BAR; PG8_SCHED;
	v_mfma_f32_16x16x32_bf16 v[62:65], v[50:53], v[192:195], v[62:65]
	v_mfma_f32_16x16x32_bf16 v[58:61], v[150:153], v[192:195], v[58:61]
	v_mfma_f32_16x16x32_bf16 v[42:45], v[50:53], v[200:203], v[42:45]
	v_mfma_f32_16x16x32_bf16 v[38:41], v[150:153], v[200:203], v[38:41]
	v_mfma_f32_16x16x32_bf16 v[26:29], v[50:53], v[208:211], v[26:29]
	v_mfma_f32_16x16x32_bf16 v[22:25], v[150:153], v[208:211], v[22:25]
	v_mfma_f32_16x16x32_bf16 v[10:13], v[50:53], v[216:219], v[10:13]
	v_mfma_f32_16x16x32_bf16 v[6:9], v[150:153], v[216:219], v[6:9]
	v_mfma_f32_16x16x32_bf16 v[62:65], v[102:105], v[196:199], v[62:65]
	v_mfma_f32_16x16x32_bf16 v[58:61], v[154:157], v[196:199], v[58:61]
	v_mfma_f32_16x16x32_bf16 v[42:45], v[102:105], v[204:207], v[42:45]
	v_mfma_f32_16x16x32_bf16 v[38:41], v[154:157], v[204:207], v[38:41]
	v_mfma_f32_16x16x32_bf16 v[26:29], v[102:105], v[212:215], v[26:29]
	v_mfma_f32_16x16x32_bf16 v[22:25], v[154:157], v[212:215], v[22:25]
	v_mfma_f32_16x16x32_bf16 v[10:13], v[102:105], v[220:223], v[10:13]
	v_mfma_f32_16x16x32_bf16 v[6:9], v[154:157], v[220:223], v[6:9]
	v_mfma_f32_16x16x32_bf16 v[54:57], v[184:187], v[192:195], v[54:57]
	v_mfma_f32_16x16x32_bf16 v[46:49], v[158:161], v[200:203], v[46:49]
	v_mfma_f32_16x16x32_bf16 v[34:37], v[184:187], v[200:203], v[34:37]
	v_mfma_f32_16x16x32_bf16 v[30:33], v[158:161], v[208:211], v[30:33]
	v_mfma_f32_16x16x32_bf16 v[18:21], v[184:187], v[208:211], v[18:21]
	v_mfma_f32_16x16x32_bf16 v[14:17], v[158:161], v[216:219], v[14:17]
	v_mfma_f32_16x16x32_bf16 v[2:5], v[184:187], v[216:219], v[2:5]
	v_mfma_f32_16x16x32_bf16 v[50:53], v[158:161], v[192:195], v[66:69]
	v_mfma_f32_16x16x32_bf16 v[54:57], v[188:191], v[196:199], v[54:57]
	v_mfma_f32_16x16x32_bf16 v[46:49], v[180:183], v[204:207], v[46:49]
	v_mfma_f32_16x16x32_bf16 v[34:37], v[188:191], v[204:207], v[34:37]
	v_mfma_f32_16x16x32_bf16 v[30:33], v[180:183], v[212:215], v[30:33]
	v_mfma_f32_16x16x32_bf16 v[18:21], v[188:191], v[212:215], v[18:21]
	v_mfma_f32_16x16x32_bf16 v[14:17], v[180:183], v[220:223], v[14:17]
	v_mfma_f32_16x16x32_bf16 v[2:5], v[188:191], v[220:223], v[2:5]
	v_mfma_f32_16x16x32_bf16 v[50:53], v[180:183], v[196:199], v[50:53]
	s_barrier
	s_setprio 0
	s_add_i32 s83, 0, 0x18000
	s_add_i32 s84, 0, 0x1c000
	v_add_u32_e32 v154, s83, v165
	v_add_u32_e32 v167, s84, v165
	ds_read_b128 v[66:69], v154
	ds_read_b128 v[102:105], v154 offset:1024
	ds_read_b128 v[150:153], v154 offset:2048
	ds_read_b128 v[154:157], v154 offset:3072
	ds_read_b128 v[158:161], v167
	ds_read_b128 v[180:183], v167 offset:1024
	ds_read_b128 v[184:187], v167 offset:2048
	ds_read_b128 v[188:191], v167 offset:3072
	s_add_u32 s14, s14, 0x40000
	s_addc_u32 s15, s15, 0
	s_mov_b32 m0, s91
	v_lshl_add_u64 v[230:231], s[14:15], 0, v[138:139]
	ds_read_b128 v[192:195], v166 offset:32768
	ds_read_b128 v[196:199], v166 offset:33792
	ds_read_b128 v[200:203], v166 offset:34816
	ds_read_b128 v[204:207], v166 offset:35840
	ds_read_b128 v[208:211], v166 offset:36864
	ds_read_b128 v[212:215], v166 offset:37888
	ds_read_b128 v[216:219], v166 offset:38912
	ds_read_b128 v[220:223], v166 offset:39936
	global_load_lds_dwordx4 v[230:231], off
	v_lshl_add_u64 v[230:231], s[14:15], 0, v[142:143]
	s_mov_b32 m0, s68
	s_nop 0
	global_load_lds_dwordx4 v[230:231], off
	s_waitcnt vmcnt(8) lgkmcnt(0)
	s_setprio 1
	s_barrier
	v_mfma_f32_16x16x32_bf16 v[130:133], v[66:69], v[192:195], v[130:133]
	v_mfma_f32_16x16x32_bf16 v[126:129], v[150:153], v[192:195], v[126:129]
	v_mfma_f32_16x16x32_bf16 v[114:117], v[66:69], v[200:203], v[114:117]
	v_mfma_f32_16x16x32_bf16 v[110:113], v[150:153], v[200:203], v[110:113]
	v_mfma_f32_16x16x32_bf16 v[94:97], v[66:69], v[208:211], v[94:97]
	v_mfma_f32_16x16x32_bf16 v[90:93], v[150:153], v[208:211], v[90:93]
	v_mfma_f32_16x16x32_bf16 v[78:81], v[66:69], v[216:219], v[78:81]
	v_mfma_f32_16x16x32_bf16 v[74:77], v[150:153], v[216:219], v[74:77]
	v_mfma_f32_16x16x32_bf16 v[130:133], v[102:105], v[196:199], v[130:133]
	v_mfma_f32_16x16x32_bf16 v[126:129], v[154:157], v[196:199], v[126:129]
	v_mfma_f32_16x16x32_bf16 v[114:117], v[102:105], v[204:207], v[114:117]
	v_mfma_f32_16x16x32_bf16 v[110:113], v[154:157], v[204:207], v[110:113]
	v_mfma_f32_16x16x32_bf16 v[94:97], v[102:105], v[212:215], v[94:97]
	v_mfma_f32_16x16x32_bf16 v[90:93], v[154:157], v[212:215], v[90:93]
	v_mfma_f32_16x16x32_bf16 v[78:81], v[102:105], v[220:223], v[78:81]
	v_mfma_f32_16x16x32_bf16 v[74:77], v[154:157], v[220:223], v[74:77]
	v_mfma_f32_16x16x32_bf16 v[134:137], v[158:161], v[192:195], v[134:137]
	v_mfma_f32_16x16x32_bf16 v[122:125], v[184:187], v[192:195], v[122:125]
	v_mfma_f32_16x16x32_bf16 v[118:121], v[158:161], v[200:203], v[118:121]
	v_mfma_f32_16x16x32_bf16 v[106:109], v[184:187], v[200:203], v[106:109]
	v_mfma_f32_16x16x32_bf16 v[98:101], v[158:161], v[208:211], v[98:101]
	v_mfma_f32_16x16x32_bf16 v[86:89], v[184:187], v[208:211], v[86:89]
	v_mfma_f32_16x16x32_bf16 v[82:85], v[158:161], v[216:219], v[82:85]
	v_mfma_f32_16x16x32_bf16 v[70:73], v[184:187], v[216:219], v[70:73]
	v_mfma_f32_16x16x32_bf16 v[134:137], v[180:183], v[196:199], v[134:137]
	v_mfma_f32_16x16x32_bf16 v[122:125], v[188:191], v[196:199], v[122:125]
	v_mfma_f32_16x16x32_bf16 v[118:121], v[180:183], v[204:207], v[118:121]
	v_mfma_f32_16x16x32_bf16 v[106:109], v[188:191], v[204:207], v[106:109]
	v_mfma_f32_16x16x32_bf16 v[98:101], v[180:183], v[212:215], v[98:101]
	v_mfma_f32_16x16x32_bf16 v[86:89], v[188:191], v[212:215], v[86:89]
	v_mfma_f32_16x16x32_bf16 v[82:85], v[180:183], v[220:223], v[82:85]
	v_mfma_f32_16x16x32_bf16 v[70:73], v[188:191], v[220:223], v[70:73]
	s_barrier
; #define PG8_STAGE(bufoff, gbase, voff) do { _Pragma("unroll") for (int _i = 0; _i < 2; ++_i) \
;         __builtin_amdgcn_global_load_lds((const unsigned*)((const char*)(gbase) + (voff)[_i]), (LAS unsigned*)(lds + (bufoff) + ldsw + _i * 8192), 16, 0, 0); } while (0)
; #define PG8_LDA(dst, b, h) do { _Pragma("unroll") for (int m = 0; m < 4; ++m) _Pragma("unroll") for (int k = 0; k < 2; ++k) dst[m][k] = *(const LAS bf16x8*)(lds + PG8_SA(b, h) + aoff + m * 2048 + k * 1024); } while (0)
; #define PG8_MMA(ai, bj, At, Bt) do { __builtin_amdgcn_s_setprio(1); _Pragma("unroll") for (int m = 0; m < 4; ++m) _Pragma("unroll") for (int n = 0; n < 2; ++n) _Pragma("unroll") for (int k = 0; k < 2; ++k) \
;         acc[ai][bj][m][n] = __builtin_amdgcn_mfma_f32_16x16x32_bf16(Bt[n][k], At[m][k], acc[ai][bj][m][n], 0, 0, 0); __builtin_amdgcn_s_setprio(0); } while (0)
; #define PG8_WAIT_V(n) asm volatile("s_waitcnt vmcnt(" #n ")" ::: "memory")
; #define PG8_WAIT_L(n) asm volatile("s_waitcnt lgkmcnt(" #n ")" ::: "memory")
; #define PG8_BAR __builtin_amdgcn_s_barrier()
; #define PG8_SCHED __builtin_amdgcn_sched_barrier(0)
; template <class Epi, class Sched>
; __device__ __forceinline__ void gemm_phase(LAS unsigned char* lds, const Gemm g, const Sched S, const Epi E, const int tid) {
;     ...
;             PG8_LDA(At, 1, 1); PG8_STAGE(PG8_SB(1, 0), b3, voffB); PG8_STAGE(PG8_SB(1, 1), b3 + hstepB, voffB); PG8_STAGE(PG8_SA(1, 0), a3, voffA);
;             PG8_WAIT_V(8); PG8_WAIT_L(0); PG8_BAR; PG8_MMA(1, 0, At, B0); PG8_MMA(1, 1, At, B1); PG8_BAR; PG8_SCHED;
;         }
;         if (wr == 0) PG8_BAR;
	s_setprio 0
	s_add_i32 s14, s83, s37
	v_lshl_add_u64 v[162:163], v[162:163], 0, s[64:65]
	s_mov_b32 m0, s14
	ds_read_b128 v[192:195], v166 offset:49152
	ds_read_b128 v[196:199], v166 offset:50176
	ds_read_b128 v[200:203], v166 offset:51200
	ds_read_b128 v[204:207], v166 offset:52224
	ds_read_b128 v[208:211], v166 offset:53248
	ds_read_b128 v[212:215], v166 offset:54272
	ds_read_b128 v[216:219], v166 offset:55296
	ds_read_b128 v[220:223], v166 offset:56320
	global_load_lds_dwordx4 v[162:163], off
	s_add_i32 m0, s14, 0x2000
	s_add_u32 s12, s12, 0x40080
	v_lshl_add_u64 v[162:163], v[224:225], 0, s[64:65]
	s_addc_u32 s13, s13, 0
	s_add_i32 s14, s84, s37
	global_load_lds_dwordx4 v[162:163], off
	v_lshl_add_u64 v[162:163], s[12:13], 0, v[140:141]
	s_mov_b32 m0, s14
	s_nop 0
	global_load_lds_dwordx4 v[162:163], off
	v_lshl_add_u64 v[162:163], s[12:13], 0, v[144:145]
	s_add_i32 m0, s14, 0x2000
	s_nop 0
	global_load_lds_dwordx4 v[162:163], off
	v_lshl_add_u64 v[162:163], v[226:227], 0, s[64:65]
	s_mov_b32 m0, s29
	s_nop 0
	global_load_lds_dwordx4 v[162:163], off
	v_lshl_add_u64 v[162:163], v[228:229], 0, s[64:65]
	s_mov_b32 m0, s92
	s_nop 0
	global_load_lds_dwordx4 v[162:163], off
	s_waitcnt vmcnt(8) lgkmcnt(0)
	s_setprio 1
	s_barrier
	v_mfma_f32_16x16x32_bf16 v[62:65], v[66:69], v[192:195], v[62:65]
	v_mfma_f32_16x16x32_bf16 v[58:61], v[150:153], v[192:195], v[58:61]
	v_mfma_f32_16x16x32_bf16 v[42:45], v[66:69], v[200:203], v[42:45]
	v_mfma_f32_16x16x32_bf16 v[38:41], v[150:153], v[200:203], v[38:41]
	v_mfma_f32_16x16x32_bf16 v[26:29], v[66:69], v[208:211], v[26:29]
	v_mfma_f32_16x16x32_bf16 v[22:25], v[150:153], v[208:211], v[22:25]
	v_mfma_f32_16x16x32_bf16 v[10:13], v[66:69], v[216:219], v[10:13]
	v_mfma_f32_16x16x32_bf16 v[6:9], v[150:153], v[216:219], v[6:9]
	v_mfma_f32_16x16x32_bf16 v[62:65], v[102:105], v[196:199], v[62:65]
	v_mfma_f32_16x16x32_bf16 v[58:61], v[154:157], v[196:199], v[58:61]
	v_mfma_f32_16x16x32_bf16 v[42:45], v[102:105], v[204:207], v[42:45]
	v_mfma_f32_16x16x32_bf16 v[38:41], v[154:157], v[204:207], v[38:41]
	v_mfma_f32_16x16x32_bf16 v[26:29], v[102:105], v[212:215], v[26:29]
	v_mfma_f32_16x16x32_bf16 v[22:25], v[154:157], v[212:215], v[22:25]
	v_mfma_f32_16x16x32_bf16 v[10:13], v[102:105], v[220:223], v[10:13]
	v_mfma_f32_16x16x32_bf16 v[6:9], v[154:157], v[220:223], v[6:9]
	v_mfma_f32_16x16x32_bf16 v[50:53], v[158:161], v[192:195], v[50:53]
	v_mfma_f32_16x16x32_bf16 v[66:69], v[180:183], v[196:199], v[50:53]
	v_mfma_f32_16x16x32_bf16 v[50:53], v[184:187], v[192:195], v[54:57]
	v_mfma_f32_16x16x32_bf16 v[46:49], v[158:161], v[200:203], v[46:49]
	v_mfma_f32_16x16x32_bf16 v[34:37], v[184:187], v[200:203], v[34:37]
	v_mfma_f32_16x16x32_bf16 v[30:33], v[158:161], v[208:211], v[30:33]
	v_mfma_f32_16x16x32_bf16 v[18:21], v[184:187], v[208:211], v[18:21]
	v_mfma_f32_16x16x32_bf16 v[14:17], v[158:161], v[216:219], v[14:17]
	v_mfma_f32_16x16x32_bf16 v[2:5], v[184:187], v[216:219], v[2:5]
	v_mfma_f32_16x16x32_bf16 v[54:57], v[188:191], v[196:199], v[50:53]
	v_mfma_f32_16x16x32_bf16 v[46:49], v[180:183], v[204:207], v[46:49]
	v_mfma_f32_16x16x32_bf16 v[34:37], v[188:191], v[204:207], v[34:37]
	v_mfma_f32_16x16x32_bf16 v[30:33], v[180:183], v[212:215], v[30:33]
	v_mfma_f32_16x16x32_bf16 v[18:21], v[188:191], v[212:215], v[18:21]
	v_mfma_f32_16x16x32_bf16 v[14:17], v[180:183], v[220:223], v[14:17]
	v_mfma_f32_16x16x32_bf16 v[2:5], v[188:191], v[220:223], v[2:5]
	s_barrier
	s_setprio 0
	s_add_i32 s82, s82, 2
	s_add_u32 s49, s49, 0x100
	s_addc_u32 s62, s62, 0
	s_add_u32 s10, s10, 0x100
	s_addc_u32 s11, s11, 0
	s_cmp_gt_u32 s82, 13
	s_cbranch_scc0 .LBB0_471
	s_and_b64 vcc, exec, s[18:19]
	s_cbranch_vccz .LBB0_474
	s_barrier

; #define PG8_STAGE(bufoff, gbase, voff) do { _Pragma("unroll") for (int _i = 0; _i < 2; ++_i) \
;         __builtin_amdgcn_global_load_lds((const unsigned*)((const char*)(gbase) + (voff)[_i]), (LAS unsigned*)(lds + (bufoff) + ldsw + _i * 8192), 16, 0, 0); } while (0)
; #define PG8_LDA(dst, b, h) do { _Pragma("unroll") for (int m = 0; m < 4; ++m) _Pragma("unroll") for (int k = 0; k < 2; ++k) dst[m][k] = *(const LAS bf16x8*)(lds + PG8_SA(b, h) + aoff + m * 2048 + k * 1024); } while (0)
; #define PG8_LDB(dst, b, h) do { _Pragma("unroll") for (int n = 0; n < 2; ++n) _Pragma("unroll") for (int k = 0; k < 2; ++k) dst[n][k] = *(const LAS bf16x8*)(lds + PG8_SB(b, h) + boff + n * 2048 + k * 1024); } while (0)
; #define PG8_MMA(ai, bj, At, Bt) do { __builtin_amdgcn_s_setprio(1); _Pragma("unroll") for (int m = 0; m < 4; ++m) _Pragma("unroll") for (int n = 0; n < 2; ++n) _Pragma("unroll") for (int k = 0; k < 2; ++k) \
;         acc[ai][bj][m][n] = __builtin_amdgcn_mfma_f32_16x16x32_bf16(Bt[n][k], At[m][k], acc[ai][bj][m][n], 0, 0, 0); __builtin_amdgcn_s_setprio(0); } while (0)
; #define PG8_WAIT_V(n) asm volatile("s_waitcnt vmcnt(" #n ")" ::: "memory")
; #define PG8_WAIT_L(n) asm volatile("s_waitcnt lgkmcnt(" #n ")" ::: "memory")
; #define PG8_BAR __builtin_amdgcn_s_barrier()
; #define PG8_SCHED __builtin_amdgcn_sched_barrier(0)
; template <class Epi, class Sched>
; __device__ __forceinline__ void gemm_phase(LAS unsigned char* lds, const Gemm g, const Sched S, const Epi E, const int tid) {
;     ...
;             const bool last = (t == nt - 2);
;             const char* a1 = cA + (size_t)(t + 1) * kstep;
;             const char* a2 = last ? nA : cA + (size_t)(t + 2) * kstep; const char* b2 = last ? nB : cB + (size_t)(t + 2) * kstep;
;             const char* a3 = a2 + kstep; const char* b3 = b2 + kstep;
;             PG8_LDB(B0, 0, 0); PG8_LDB(B1, 0, 1); PG8_SCHED; PG8_LDA(At, 0, 0); PG8_STAGE(PG8_SA(1, 1), a1 + hstepA, voffA);
;             PG8_WAIT_V(8); PG8_WAIT_L(0); PG8_BAR; PG8_MMA(0, 0, At, B0); PG8_MMA(0, 1, At, B1); PG8_BAR; PG8_SCHED;
;             PG8_LDA(At, 0, 1); PG8_STAGE(PG8_SB(0, 0), b2, voffB); PG8_STAGE(PG8_SB(0, 1), b2 + hstepB, voffB); PG8_STAGE(PG8_SA(0, 0), a2, voffA);
;             PG8_WAIT_V(8); PG8_WAIT_L(0); PG8_BAR; PG8_MMA(1, 0, At, B0); PG8_MMA(1, 1, At, B1); PG8_BAR; PG8_SCHED;
.LBB0_778:
	s_add_i32 s94, s20, 2
	s_add_u32 s95, s18, 0x80
	s_addc_u32 s21, s19, 0
	s_add_i32 vcc_lo, 0, 0x10000
	s_cmp_eq_u32 s69, s20
	s_cselect_b32 s21, s9, s21
	s_cselect_b32 s20, s8, s95
	s_cselect_b32 s97, s17, s93
	s_cselect_b32 s96, s16, s92
	s_add_i32 s95, 0, 0x14000
	v_add_u32_e32 v142, vcc_lo, v198
	v_add_u32_e32 v167, s95, v198
	ds_read_b128 v[126:129], v142
	ds_read_b128 v[134:137], v142 offset:1024
	ds_read_b128 v[138:141], v142 offset:2048
	ds_read_b128 v[142:145], v142 offset:3072
	ds_read_b128 v[146:149], v167
	ds_read_b128 v[150:153], v167 offset:1024
	ds_read_b128 v[154:157], v167 offset:2048
	ds_read_b128 v[186:189], v167 offset:3072
	v_lshl_add_u64 v[224:225], s[18:19], 0, v[184:185]
	s_add_i32 m0, s37, 0xc000
	ds_read_b128 v[190:193], v199
	ds_read_b128 v[194:197], v199 offset:1024
	ds_read_b128 v[200:203], v199 offset:2048
	ds_read_b128 v[204:207], v199 offset:3072
	ds_read_b128 v[208:211], v199 offset:4096
	ds_read_b128 v[212:215], v199 offset:5120
	ds_read_b128 v[216:219], v199 offset:6144
	ds_read_b128 v[220:223], v199 offset:7168
	global_load_lds_dwordx4 v[224:225], off
	v_lshl_add_u64 v[224:225], s[18:19], 0, v[182:183]
	s_add_i32 m0, s37, 0xe000
	s_nop 0
	global_load_lds_dwordx4 v[224:225], off
	s_waitcnt vmcnt(8) lgkmcnt(0)
	s_setprio 1
	s_barrier
	v_mfma_f32_16x16x32_bf16 v[130:133], v[126:129], v[190:193], v[130:133]
	v_mfma_f32_16x16x32_bf16 v[122:125], v[138:141], v[190:193], v[122:125]
	v_mfma_f32_16x16x32_bf16 v[110:113], v[126:129], v[200:203], v[110:113]
	v_mfma_f32_16x16x32_bf16 v[106:109], v[138:141], v[200:203], v[106:109]
	v_mfma_f32_16x16x32_bf16 v[94:97], v[126:129], v[208:211], v[94:97]
	v_mfma_f32_16x16x32_bf16 v[90:93], v[138:141], v[208:211], v[90:93]
	v_mfma_f32_16x16x32_bf16 v[78:81], v[126:129], v[216:219], v[78:81]
	v_mfma_f32_16x16x32_bf16 v[74:77], v[138:141], v[216:219], v[74:77]
	v_mfma_f32_16x16x32_bf16 v[130:133], v[134:137], v[194:197], v[130:133]
	v_mfma_f32_16x16x32_bf16 v[122:125], v[142:145], v[194:197], v[122:125]
	v_mfma_f32_16x16x32_bf16 v[110:113], v[134:137], v[204:207], v[110:113]
	v_mfma_f32_16x16x32_bf16 v[106:109], v[142:145], v[204:207], v[106:109]
	v_mfma_f32_16x16x32_bf16 v[94:97], v[134:137], v[212:215], v[94:97]
	v_mfma_f32_16x16x32_bf16 v[90:93], v[142:145], v[212:215], v[90:93]
	v_mfma_f32_16x16x32_bf16 v[78:81], v[134:137], v[220:223], v[78:81]
	v_mfma_f32_16x16x32_bf16 v[74:77], v[142:145], v[220:223], v[74:77]
	v_mfma_f32_16x16x32_bf16 v[118:121], v[146:149], v[190:193], v[118:121]
	v_mfma_f32_16x16x32_bf16 v[114:117], v[154:157], v[190:193], v[114:117]
	v_mfma_f32_16x16x32_bf16 v[102:105], v[146:149], v[200:203], v[102:105]
	v_mfma_f32_16x16x32_bf16 v[98:101], v[154:157], v[200:203], v[98:101]
	v_mfma_f32_16x16x32_bf16 v[86:89], v[146:149], v[208:211], v[86:89]
	v_mfma_f32_16x16x32_bf16 v[82:85], v[154:157], v[208:211], v[82:85]
	v_mfma_f32_16x16x32_bf16 v[70:73], v[146:149], v[216:219], v[70:73]
	v_mfma_f32_16x16x32_bf16 v[66:69], v[154:157], v[216:219], v[66:69]
	v_mfma_f32_16x16x32_bf16 v[118:121], v[150:153], v[194:197], v[118:121]
	v_mfma_f32_16x16x32_bf16 v[114:117], v[186:189], v[194:197], v[114:117]
	v_mfma_f32_16x16x32_bf16 v[102:105], v[150:153], v[204:207], v[102:105]
	v_mfma_f32_16x16x32_bf16 v[98:101], v[186:189], v[204:207], v[98:101]
	v_mfma_f32_16x16x32_bf16 v[86:89], v[150:153], v[212:215], v[86:89]
	v_mfma_f32_16x16x32_bf16 v[82:85], v[186:189], v[212:215], v[82:85]
	v_mfma_f32_16x16x32_bf16 v[70:73], v[150:153], v[220:223], v[70:73]
	v_mfma_f32_16x16x32_bf16 v[66:69], v[186:189], v[220:223], v[66:69]
	s_barrier
	s_setprio 0
	s_add_i32 vcc_lo, vcc_lo, s29
	v_lshl_add_u64 v[224:225], s[96:97], 0, v[160:161]
	s_mov_b32 m0, vcc_lo
	ds_read_b128 v[190:193], v199 offset:16384
	ds_read_b128 v[194:197], v199 offset:17408
	ds_read_b128 v[200:203], v199 offset:18432
	ds_read_b128 v[204:207], v199 offset:19456
	ds_read_b128 v[208:211], v199 offset:20480
	ds_read_b128 v[212:215], v199 offset:21504
	ds_read_b128 v[216:219], v199 offset:22528
	ds_read_b128 v[220:223], v199 offset:23552
	global_load_lds_dwordx4 v[224:225], off
	s_add_i32 m0, vcc_lo, 0x2000
	v_lshl_add_u64 v[226:227], s[96:97], 0, v[164:165]
	s_add_u32 s96, s96, s62
	s_addc_u32 s97, s97, 0
	s_add_i32 s95, s95, s29
	global_load_lds_dwordx4 v[226:227], off
	v_lshl_add_u64 v[228:229], s[96:97], 0, v[160:161]
	s_mov_b32 m0, s95
	v_lshl_add_u64 v[230:231], s[96:97], 0, v[164:165]
	global_load_lds_dwordx4 v[228:229], off
	s_add_i32 m0, s95, 0x2000
	v_lshl_add_u64 v[232:233], s[20:21], 0, v[158:159]
	global_load_lds_dwordx4 v[230:231], off
	s_mov_b32 m0, s37
	v_lshl_add_u64 v[234:235], s[20:21], 0, v[162:163]
	global_load_lds_dwordx4 v[232:233], off
	s_mov_b32 m0, s40
	s_nop 0
	global_load_lds_dwordx4 v[234:235], off
	s_waitcnt vmcnt(8) lgkmcnt(0)
	s_setprio 1
	s_barrier
; #define PG8_STAGE(bufoff, gbase, voff) do { _Pragma("unroll") for (int _i = 0; _i < 2; ++_i) \
;         __builtin_amdgcn_global_load_lds((const unsigned*)((const char*)(gbase) + (voff)[_i]), (LAS unsigned*)(lds + (bufoff) + ldsw + _i * 8192), 16, 0, 0); } while (0)
; #define PG8_LDA(dst, b, h) do { _Pragma("unroll") for (int m = 0; m < 4; ++m) _Pragma("unroll") for (int k = 0; k < 2; ++k) dst[m][k] = *(const LAS bf16x8*)(lds + PG8_SA(b, h) + aoff + m * 2048 + k * 1024); } while (0)
; #define PG8_LDB(dst, b, h) do { _Pragma("unroll") for (int n = 0; n < 2; ++n) _Pragma("unroll") for (int k = 0; k < 2; ++k) dst[n][k] = *(const LAS bf16x8*)(lds + PG8_SB(b, h) + boff + n * 2048 + k * 1024); } while (0)
; #define PG8_MMA(ai, bj, At, Bt) do { __builtin_amdgcn_s_setprio(1); _Pragma("unroll") for (int m = 0; m < 4; ++m) _Pragma("unroll") for (int n = 0; n < 2; ++n) _Pragma("unroll") for (int k = 0; k < 2; ++k) \
;         acc[ai][bj][m][n] = __builtin_amdgcn_mfma_f32_16x16x32_bf16(Bt[n][k], At[m][k], acc[ai][bj][m][n], 0, 0, 0); __builtin_amdgcn_s_setprio(0); } while (0)
; #define PG8_WAIT_V(n) asm volatile("s_waitcnt vmcnt(" #n ")" ::: "memory")
; #define PG8_WAIT_L(n) asm volatile("s_waitcnt lgkmcnt(" #n ")" ::: "memory")
; #define PG8_BAR __builtin_amdgcn_s_barrier()
; #define PG8_SCHED __builtin_amdgcn_sched_barrier(0)
; template <class Epi, class Sched>
; __device__ __forceinline__ void gemm_phase(LAS unsigned char* lds, const Gemm g, const Sched S, const Epi E, const int tid) {
;     ...
;             PG8_WAIT_V(8); PG8_WAIT_L(0); PG8_BAR; PG8_MMA(1, 0, At, B0); PG8_MMA(1, 1, At, B1); PG8_BAR; PG8_SCHED;
;             PG8_LDB(B0, 1, 0); PG8_LDB(B1, 1, 1); PG8_SCHED; PG8_LDA(At, 1, 0); PG8_STAGE(PG8_SA(0, 1), a2 + hstepA, voffA);
;             PG8_WAIT_V(8); PG8_WAIT_L(0); PG8_BAR; PG8_MMA(0, 0, At, B0); PG8_MMA(0, 1, At, B1); PG8_BAR; PG8_SCHED;
	v_mfma_f32_16x16x32_bf16 v[62:65], v[126:129], v[190:193], v[62:65]
	v_mfma_f32_16x16x32_bf16 v[58:61], v[138:141], v[190:193], v[58:61]
	v_mfma_f32_16x16x32_bf16 v[46:49], v[126:129], v[200:203], v[46:49]
	v_mfma_f32_16x16x32_bf16 v[42:45], v[138:141], v[200:203], v[42:45]
	v_mfma_f32_16x16x32_bf16 v[30:33], v[126:129], v[208:211], v[30:33]
	v_mfma_f32_16x16x32_bf16 v[26:29], v[138:141], v[208:211], v[26:29]
	v_mfma_f32_16x16x32_bf16 v[14:17], v[126:129], v[216:219], v[14:17]
	v_mfma_f32_16x16x32_bf16 v[10:13], v[138:141], v[216:219], v[10:13]
	v_mfma_f32_16x16x32_bf16 v[62:65], v[134:137], v[194:197], v[62:65]
	v_mfma_f32_16x16x32_bf16 v[58:61], v[142:145], v[194:197], v[58:61]
	v_mfma_f32_16x16x32_bf16 v[46:49], v[134:137], v[204:207], v[46:49]
	v_mfma_f32_16x16x32_bf16 v[42:45], v[142:145], v[204:207], v[42:45]
	v_mfma_f32_16x16x32_bf16 v[30:33], v[134:137], v[212:215], v[30:33]
	v_mfma_f32_16x16x32_bf16 v[26:29], v[142:145], v[212:215], v[26:29]
	v_mfma_f32_16x16x32_bf16 v[14:17], v[134:137], v[220:223], v[14:17]
	v_mfma_f32_16x16x32_bf16 v[10:13], v[142:145], v[220:223], v[10:13]
	v_mfma_f32_16x16x32_bf16 v[54:57], v[146:149], v[190:193], v[54:57]
	v_mfma_f32_16x16x32_bf16 v[50:53], v[154:157], v[190:193], v[50:53]
	v_mfma_f32_16x16x32_bf16 v[38:41], v[146:149], v[200:203], v[38:41]
	v_mfma_f32_16x16x32_bf16 v[34:37], v[154:157], v[200:203], v[34:37]
	v_mfma_f32_16x16x32_bf16 v[22:25], v[146:149], v[208:211], v[22:25]
	v_mfma_f32_16x16x32_bf16 v[18:21], v[154:157], v[208:211], v[18:21]
	v_mfma_f32_16x16x32_bf16 v[6:9], v[146:149], v[216:219], v[6:9]
	v_mfma_f32_16x16x32_bf16 v[2:5], v[154:157], v[216:219], v[2:5]
	v_mfma_f32_16x16x32_bf16 v[54:57], v[150:153], v[194:197], v[54:57]
	v_mfma_f32_16x16x32_bf16 v[50:53], v[186:189], v[194:197], v[50:53]
	v_mfma_f32_16x16x32_bf16 v[38:41], v[150:153], v[204:207], v[38:41]
	v_mfma_f32_16x16x32_bf16 v[34:37], v[186:189], v[204:207], v[34:37]
	v_mfma_f32_16x16x32_bf16 v[22:25], v[150:153], v[212:215], v[22:25]
	v_mfma_f32_16x16x32_bf16 v[18:21], v[186:189], v[212:215], v[18:21]
	v_mfma_f32_16x16x32_bf16 v[6:9], v[150:153], v[220:223], v[6:9]
	v_mfma_f32_16x16x32_bf16 v[2:5], v[186:189], v[220:223], v[2:5]
	s_barrier
	s_setprio 0
	s_add_i32 s95, 0, 0x18000
	s_add_i32 s96, 0, 0x1c000
	v_add_u32_e32 v142, s95, v198
	v_add_u32_e32 v167, s96, v198
	ds_read_b128 v[126:129], v142
	ds_read_b128 v[134:137], v142 offset:1024
	ds_read_b128 v[138:141], v142 offset:2048
	ds_read_b128 v[142:145], v142 offset:3072
	ds_read_b128 v[146:149], v167
	ds_read_b128 v[150:153], v167 offset:1024
	ds_read_b128 v[154:157], v167 offset:2048
	ds_read_b128 v[186:189], v167 offset:3072
	s_add_u32 s20, s20, s62
	s_addc_u32 s21, s21, 0
	s_mov_b32 m0, s41
	v_lshl_add_u64 v[246:247], s[20:21], 0, v[158:159]
	ds_read_b128 v[190:193], v199 offset:32768
	ds_read_b128 v[194:197], v199 offset:33792
	ds_read_b128 v[200:203], v199 offset:34816
	ds_read_b128 v[204:207], v199 offset:35840
	ds_read_b128 v[208:211], v199 offset:36864
	ds_read_b128 v[212:215], v199 offset:37888
	ds_read_b128 v[216:219], v199 offset:38912
	ds_read_b128 v[220:223], v199 offset:39936
	global_load_lds_dwordx4 v[246:247], off
	v_lshl_add_u64 v[246:247], s[20:21], 0, v[162:163]
	s_mov_b32 m0, s42
	s_nop 0
	global_load_lds_dwordx4 v[246:247], off
	s_waitcnt vmcnt(8) lgkmcnt(0)
	s_setprio 1
	s_barrier
	v_mfma_f32_16x16x32_bf16 v[130:133], v[126:129], v[190:193], v[130:133]
	v_mfma_f32_16x16x32_bf16 v[122:125], v[138:141], v[190:193], v[122:125]
	v_mfma_f32_16x16x32_bf16 v[110:113], v[126:129], v[200:203], v[110:113]
	v_mfma_f32_16x16x32_bf16 v[106:109], v[138:141], v[200:203], v[106:109]
	v_mfma_f32_16x16x32_bf16 v[94:97], v[126:129], v[208:211], v[94:97]
	v_mfma_f32_16x16x32_bf16 v[90:93], v[138:141], v[208:211], v[90:93]
	v_mfma_f32_16x16x32_bf16 v[78:81], v[126:129], v[216:219], v[78:81]
	v_mfma_f32_16x16x32_bf16 v[74:77], v[138:141], v[216:219], v[74:77]
	v_mfma_f32_16x16x32_bf16 v[130:133], v[134:137], v[194:197], v[130:133]
	v_mfma_f32_16x16x32_bf16 v[122:125], v[142:145], v[194:197], v[122:125]
	v_mfma_f32_16x16x32_bf16 v[110:113], v[134:137], v[204:207], v[110:113]
	v_mfma_f32_16x16x32_bf16 v[106:109], v[142:145], v[204:207], v[106:109]
	v_mfma_f32_16x16x32_bf16 v[94:97], v[134:137], v[212:215], v[94:97]
	v_mfma_f32_16x16x32_bf16 v[90:93], v[142:145], v[212:215], v[90:93]
	v_mfma_f32_16x16x32_bf16 v[78:81], v[134:137], v[220:223], v[78:81]
	v_mfma_f32_16x16x32_bf16 v[74:77], v[142:145], v[220:223], v[74:77]
	v_mfma_f32_16x16x32_bf16 v[118:121], v[146:149], v[190:193], v[118:121]
	v_mfma_f32_16x16x32_bf16 v[114:117], v[154:157], v[190:193], v[114:117]
	v_mfma_f32_16x16x32_bf16 v[102:105], v[146:149], v[200:203], v[102:105]
	v_mfma_f32_16x16x32_bf16 v[98:101], v[154:157], v[200:203], v[98:101]
	v_mfma_f32_16x16x32_bf16 v[86:89], v[146:149], v[208:211], v[86:89]
	v_mfma_f32_16x16x32_bf16 v[82:85], v[154:157], v[208:211], v[82:85]
	v_mfma_f32_16x16x32_bf16 v[70:73], v[146:149], v[216:219], v[70:73]
	v_mfma_f32_16x16x32_bf16 v[66:69], v[154:157], v[216:219], v[66:69]
	v_mfma_f32_16x16x32_bf16 v[118:121], v[150:153], v[194:197], v[118:121]
	v_mfma_f32_16x16x32_bf16 v[114:117], v[186:189], v[194:197], v[114:117]
	v_mfma_f32_16x16x32_bf16 v[102:105], v[150:153], v[204:207], v[102:105]
	v_mfma_f32_16x16x32_bf16 v[98:101], v[186:189], v[204:207], v[98:101]
	v_mfma_f32_16x16x32_bf16 v[86:89], v[150:153], v[212:215], v[86:89]
	v_mfma_f32_16x16x32_bf16 v[82:85], v[186:189], v[212:215], v[82:85]
	v_mfma_f32_16x16x32_bf16 v[70:73], v[150:153], v[220:223], v[70:73]
	v_mfma_f32_16x16x32_bf16 v[66:69], v[186:189], v[220:223], v[66:69]
	s_barrier
; #define PG8_STAGE(bufoff, gbase, voff) do { _Pragma("unroll") for (int _i = 0; _i < 2; ++_i) \
;         __builtin_amdgcn_global_load_lds((const unsigned*)((const char*)(gbase) + (voff)[_i]), (LAS unsigned*)(lds + (bufoff) + ldsw + _i * 8192), 16, 0, 0); } while (0)
; #define PG8_LDA(dst, b, h) do { _Pragma("unroll") for (int m = 0; m < 4; ++m) _Pragma("unroll") for (int k = 0; k < 2; ++k) dst[m][k] = *(const LAS bf16x8*)(lds + PG8_SA(b, h) + aoff + m * 2048 + k * 1024); } while (0)
; #define PG8_MMA(ai, bj, At, Bt) do { __builtin_amdgcn_s_setprio(1); _Pragma("unroll") for (int m = 0; m < 4; ++m) _Pragma("unroll") for (int n = 0; n < 2; ++n) _Pragma("unroll") for (int k = 0; k < 2; ++k) \
;         acc[ai][bj][m][n] = __builtin_amdgcn_mfma_f32_16x16x32_bf16(Bt[n][k], At[m][k], acc[ai][bj][m][n], 0, 0, 0); __builtin_amdgcn_s_setprio(0); } while (0)
; #define PG8_WAIT_V(n) asm volatile("s_waitcnt vmcnt(" #n ")" ::: "memory")
; #define PG8_WAIT_L(n) asm volatile("s_waitcnt lgkmcnt(" #n ")" ::: "memory")
; #define PG8_BAR __builtin_amdgcn_s_barrier()
; #define PG8_SCHED __builtin_amdgcn_sched_barrier(0)
; template <class Epi, class Sched>
; __device__ __forceinline__ void gemm_phase(LAS unsigned char* lds, const Gemm g, const Sched S, const Epi E, const int tid) {
;     ...
;             PG8_LDA(At, 1, 1); PG8_STAGE(PG8_SB(1, 0), b3, voffB); PG8_STAGE(PG8_SB(1, 1), b3 + hstepB, voffB); PG8_STAGE(PG8_SA(1, 0), a3, voffA);
;             PG8_WAIT_V(8); PG8_WAIT_L(0); PG8_BAR; PG8_MMA(1, 0, At, B0); PG8_MMA(1, 1, At, B1); PG8_BAR; PG8_SCHED;
;         }
;         if (wr == 0) PG8_BAR;
	s_setprio 0
	s_add_i32 s20, s95, s29
	v_lshl_add_u64 v[224:225], v[224:225], 0, s[64:65]
	s_mov_b32 m0, s20
	ds_read_b128 v[190:193], v199 offset:49152
	ds_read_b128 v[194:197], v199 offset:50176
	ds_read_b128 v[200:203], v199 offset:51200
	ds_read_b128 v[204:207], v199 offset:52224
	ds_read_b128 v[208:211], v199 offset:53248
	ds_read_b128 v[212:215], v199 offset:54272
	ds_read_b128 v[216:219], v199 offset:55296
	ds_read_b128 v[220:223], v199 offset:56320
	global_load_lds_dwordx4 v[224:225], off
	v_lshl_add_u64 v[224:225], v[226:227], 0, s[64:65]
	s_add_i32 m0, s20, 0x2000
	s_add_i32 s20, s96, s29
	global_load_lds_dwordx4 v[224:225], off
	v_lshl_add_u64 v[224:225], v[228:229], 0, s[64:65]
	s_mov_b32 m0, s20
	s_nop 0
	global_load_lds_dwordx4 v[224:225], off
	v_lshl_add_u64 v[224:225], v[230:231], 0, s[64:65]
	s_add_i32 m0, s20, 0x2000
	s_nop 0
	global_load_lds_dwordx4 v[224:225], off
	v_lshl_add_u64 v[224:225], v[232:233], 0, s[64:65]
	s_mov_b32 m0, s45
	s_nop 0
	global_load_lds_dwordx4 v[224:225], off
	v_lshl_add_u64 v[224:225], v[234:235], 0, s[64:65]
	s_mov_b32 m0, s46
	s_nop 0
	global_load_lds_dwordx4 v[224:225], off
	s_waitcnt vmcnt(8) lgkmcnt(0)
	s_setprio 1
	s_barrier
	v_mfma_f32_16x16x32_bf16 v[62:65], v[126:129], v[190:193], v[62:65]
	v_mfma_f32_16x16x32_bf16 v[58:61], v[138:141], v[190:193], v[58:61]
	v_mfma_f32_16x16x32_bf16 v[46:49], v[126:129], v[200:203], v[46:49]
	v_mfma_f32_16x16x32_bf16 v[42:45], v[138:141], v[200:203], v[42:45]
	v_mfma_f32_16x16x32_bf16 v[30:33], v[126:129], v[208:211], v[30:33]
	v_mfma_f32_16x16x32_bf16 v[26:29], v[138:141], v[208:211], v[26:29]
	v_mfma_f32_16x16x32_bf16 v[14:17], v[126:129], v[216:219], v[14:17]
	v_mfma_f32_16x16x32_bf16 v[10:13], v[138:141], v[216:219], v[10:13]
	v_mfma_f32_16x16x32_bf16 v[62:65], v[134:137], v[194:197], v[62:65]
	v_mfma_f32_16x16x32_bf16 v[58:61], v[142:145], v[194:197], v[58:61]
	v_mfma_f32_16x16x32_bf16 v[46:49], v[134:137], v[204:207], v[46:49]
	v_mfma_f32_16x16x32_bf16 v[42:45], v[142:145], v[204:207], v[42:45]
	v_mfma_f32_16x16x32_bf16 v[30:33], v[134:137], v[212:215], v[30:33]
	v_mfma_f32_16x16x32_bf16 v[26:29], v[142:145], v[212:215], v[26:29]
	v_mfma_f32_16x16x32_bf16 v[14:17], v[134:137], v[220:223], v[14:17]
	v_mfma_f32_16x16x32_bf16 v[10:13], v[142:145], v[220:223], v[10:13]
	v_mfma_f32_16x16x32_bf16 v[54:57], v[146:149], v[190:193], v[54:57]
	v_mfma_f32_16x16x32_bf16 v[50:53], v[154:157], v[190:193], v[50:53]
	v_mfma_f32_16x16x32_bf16 v[38:41], v[146:149], v[200:203], v[38:41]
	v_mfma_f32_16x16x32_bf16 v[34:37], v[154:157], v[200:203], v[34:37]
	v_mfma_f32_16x16x32_bf16 v[22:25], v[146:149], v[208:211], v[22:25]
	v_mfma_f32_16x16x32_bf16 v[18:21], v[154:157], v[208:211], v[18:21]
	v_mfma_f32_16x16x32_bf16 v[6:9], v[146:149], v[216:219], v[6:9]
	v_mfma_f32_16x16x32_bf16 v[2:5], v[154:157], v[216:219], v[2:5]
	v_mfma_f32_16x16x32_bf16 v[54:57], v[150:153], v[194:197], v[54:57]
	v_mfma_f32_16x16x32_bf16 v[50:53], v[186:189], v[194:197], v[50:53]
	v_mfma_f32_16x16x32_bf16 v[38:41], v[150:153], v[204:207], v[38:41]
	v_mfma_f32_16x16x32_bf16 v[34:37], v[186:189], v[204:207], v[34:37]
	v_mfma_f32_16x16x32_bf16 v[22:25], v[150:153], v[212:215], v[22:25]
	v_mfma_f32_16x16x32_bf16 v[18:21], v[186:189], v[212:215], v[18:21]
	v_mfma_f32_16x16x32_bf16 v[6:9], v[150:153], v[220:223], v[6:9]
	v_mfma_f32_16x16x32_bf16 v[2:5], v[186:189], v[220:223], v[2:5]
	s_barrier
	s_setprio 0
	s_add_u32 s92, s92, 0x100
	s_addc_u32 s93, s93, 0
	s_add_u32 s18, s18, 0x100
	s_addc_u32 s19, s19, 0
	s_cmp_ge_u32 s94, s47
	s_mov_b32 s20, s94
	s_cbranch_scc0 .LBB0_778
	s_and_b64 vcc, exec, s[12:13]
	s_cbranch_vccz .LBB0_781
	s_barrier

; #define PG8_STAGE(bufoff, gbase, voff) do { _Pragma("unroll") for (int _i = 0; _i < 2; ++_i) \
;         __builtin_amdgcn_global_load_lds((const unsigned*)((const char*)(gbase) + (voff)[_i]), (LAS unsigned*)(lds + (bufoff) + ldsw + _i * 8192), 16, 0, 0); } while (0)
; #define PG8_LDA(dst, b, h) do { _Pragma("unroll") for (int m = 0; m < 4; ++m) _Pragma("unroll") for (int k = 0; k < 2; ++k) dst[m][k] = *(const LAS bf16x8*)(lds + PG8_SA(b, h) + aoff + m * 2048 + k * 1024); } while (0)
; #define PG8_LDB(dst, b, h) do { _Pragma("unroll") for (int n = 0; n < 2; ++n) _Pragma("unroll") for (int k = 0; k < 2; ++k) dst[n][k] = *(const LAS bf16x8*)(lds + PG8_SB(b, h) + boff + n * 2048 + k * 1024); } while (0)
; #define PG8_MMA(ai, bj, At, Bt) do { __builtin_amdgcn_s_setprio(1); _Pragma("unroll") for (int m = 0; m < 4; ++m) _Pragma("unroll") for (int n = 0; n < 2; ++n) _Pragma("unroll") for (int k = 0; k < 2; ++k) \
;         acc[ai][bj][m][n] = __builtin_amdgcn_mfma_f32_16x16x32_bf16(Bt[n][k], At[m][k], acc[ai][bj][m][n], 0, 0, 0); __builtin_amdgcn_s_setprio(0); } while (0)
; #define PG8_WAIT_V(n) asm volatile("s_waitcnt vmcnt(" #n ")" ::: "memory")
; #define PG8_WAIT_L(n) asm volatile("s_waitcnt lgkmcnt(" #n ")" ::: "memory")
; #define PG8_BAR __builtin_amdgcn_s_barrier()
; #define PG8_SCHED __builtin_amdgcn_sched_barrier(0)
; template <class Epi, class Sched>
; __device__ __forceinline__ void gemm_phase(LAS unsigned char* lds, const Gemm g, const Sched S, const Epi E, const int tid) {
;     ...
;             const bool last = (t == nt - 2);
;             const char* a1 = cA + (size_t)(t + 1) * kstep;
;             const char* a2 = last ? nA : cA + (size_t)(t + 2) * kstep; const char* b2 = last ? nB : cB + (size_t)(t + 2) * kstep;
;             const char* a3 = a2 + kstep; const char* b3 = b2 + kstep;
;             PG8_LDB(B0, 0, 0); PG8_LDB(B1, 0, 1); PG8_SCHED; PG8_LDA(At, 0, 0); PG8_STAGE(PG8_SA(1, 1), a1 + hstepA, voffA);
;             PG8_WAIT_V(8); PG8_WAIT_L(0); PG8_BAR; PG8_MMA(0, 0, At, B0); PG8_MMA(0, 1, At, B1); PG8_BAR; PG8_SCHED;
;             PG8_LDA(At, 0, 1); PG8_STAGE(PG8_SB(0, 0), b2, voffB); PG8_STAGE(PG8_SB(0, 1), b2 + hstepB, voffB); PG8_STAGE(PG8_SA(0, 0), a2, voffA);
;             PG8_WAIT_V(8); PG8_WAIT_L(0); PG8_BAR; PG8_MMA(1, 0, At, B0); PG8_MMA(1, 1, At, B1); PG8_BAR; PG8_SCHED;
.LBB0_819:
	s_add_u32 s24, s22, 0xfffc0080
	s_addc_u32 s25, s23, -1
	s_add_i32 s85, 0, 0x10000
	s_cmp_eq_u32 s84, 12
	s_cselect_b32 s27, s9, s25
	s_cselect_b32 s26, s17, s24
	s_cselect_b32 s25, s15, s83
	s_cselect_b32 s24, s69, s82
	s_add_i32 s90, 0, 0x14000
	v_add_u32_e32 v154, s85, v165
	v_add_u32_e32 v162, s90, v165
	ds_read_b128 v[98:101], v154
	ds_read_b128 v[134:137], v154 offset:1024
	ds_read_b128 v[150:153], v154 offset:2048
	ds_read_b128 v[154:157], v154 offset:3072
	ds_read_b128 v[158:161], v162
	ds_read_b128 v[180:183], v162 offset:1024
	ds_read_b128 v[184:187], v162 offset:2048
	ds_read_b128 v[188:191], v162 offset:3072
	v_lshl_add_u64 v[162:163], s[22:23], 0, v[148:149]
	s_add_i32 m0, s40, 0xc000
	ds_read_b128 v[192:195], v166
	ds_read_b128 v[196:199], v166 offset:1024
	ds_read_b128 v[200:203], v166 offset:2048
	ds_read_b128 v[204:207], v166 offset:3072
	ds_read_b128 v[208:211], v166 offset:4096
	ds_read_b128 v[212:215], v166 offset:5120
	ds_read_b128 v[216:219], v166 offset:6144
	ds_read_b128 v[220:223], v166 offset:7168
	global_load_lds_dwordx4 v[162:163], off
	v_lshl_add_u64 v[162:163], s[22:23], 0, v[146:147]
	s_add_i32 m0, s40, 0xe000
	s_nop 0
	global_load_lds_dwordx4 v[162:163], off
	s_waitcnt vmcnt(8) lgkmcnt(0)
	s_setprio 1
	s_barrier
	v_mfma_f32_16x16x32_bf16 v[130:133], v[98:101], v[192:195], v[130:133]
	v_mfma_f32_16x16x32_bf16 v[118:121], v[150:153], v[192:195], v[118:121]
	v_mfma_f32_16x16x32_bf16 v[114:117], v[98:101], v[200:203], v[114:117]
	v_mfma_f32_16x16x32_bf16 v[102:105], v[150:153], v[200:203], v[102:105]
	v_mfma_f32_16x16x32_bf16 v[94:97], v[98:101], v[208:211], v[94:97]
	v_mfma_f32_16x16x32_bf16 v[82:85], v[150:153], v[208:211], v[82:85]
	v_mfma_f32_16x16x32_bf16 v[78:81], v[98:101], v[216:219], v[78:81]
	v_mfma_f32_16x16x32_bf16 v[66:69], v[150:153], v[216:219], v[66:69]
	v_mfma_f32_16x16x32_bf16 v[130:133], v[134:137], v[196:199], v[130:133]
	v_mfma_f32_16x16x32_bf16 v[118:121], v[154:157], v[196:199], v[118:121]
	v_mfma_f32_16x16x32_bf16 v[114:117], v[134:137], v[204:207], v[114:117]
	v_mfma_f32_16x16x32_bf16 v[102:105], v[154:157], v[204:207], v[102:105]
	v_mfma_f32_16x16x32_bf16 v[94:97], v[134:137], v[212:215], v[94:97]
	v_mfma_f32_16x16x32_bf16 v[82:85], v[154:157], v[212:215], v[82:85]
	v_mfma_f32_16x16x32_bf16 v[78:81], v[134:137], v[220:223], v[78:81]
	v_mfma_f32_16x16x32_bf16 v[66:69], v[154:157], v[220:223], v[66:69]
	v_mfma_f32_16x16x32_bf16 v[126:129], v[158:161], v[192:195], v[126:129]
	v_mfma_f32_16x16x32_bf16 v[122:125], v[184:187], v[192:195], v[122:125]
	v_mfma_f32_16x16x32_bf16 v[110:113], v[158:161], v[200:203], v[110:113]
	v_mfma_f32_16x16x32_bf16 v[106:109], v[184:187], v[200:203], v[106:109]
	v_mfma_f32_16x16x32_bf16 v[90:93], v[158:161], v[208:211], v[90:93]
	v_mfma_f32_16x16x32_bf16 v[86:89], v[184:187], v[208:211], v[86:89]
	v_mfma_f32_16x16x32_bf16 v[74:77], v[158:161], v[216:219], v[74:77]
	v_mfma_f32_16x16x32_bf16 v[70:73], v[184:187], v[216:219], v[70:73]
	v_mfma_f32_16x16x32_bf16 v[126:129], v[180:183], v[196:199], v[126:129]
	v_mfma_f32_16x16x32_bf16 v[122:125], v[188:191], v[196:199], v[122:125]
	v_mfma_f32_16x16x32_bf16 v[110:113], v[180:183], v[204:207], v[110:113]
	v_mfma_f32_16x16x32_bf16 v[106:109], v[188:191], v[204:207], v[106:109]
	v_mfma_f32_16x16x32_bf16 v[90:93], v[180:183], v[212:215], v[90:93]
	v_mfma_f32_16x16x32_bf16 v[86:89], v[188:191], v[212:215], v[86:89]
	v_mfma_f32_16x16x32_bf16 v[74:77], v[180:183], v[220:223], v[74:77]
	v_mfma_f32_16x16x32_bf16 v[70:73], v[188:191], v[220:223], v[70:73]
	s_barrier
	s_setprio 0
	s_add_i32 s85, s85, s28
	v_lshl_add_u64 v[162:163], s[24:25], 0, v[142:143]
	s_mov_b32 m0, s85
	ds_read_b128 v[192:195], v166 offset:16384
	ds_read_b128 v[196:199], v166 offset:17408
	ds_read_b128 v[200:203], v166 offset:18432
	ds_read_b128 v[204:207], v166 offset:19456
	ds_read_b128 v[208:211], v166 offset:20480
	ds_read_b128 v[212:215], v166 offset:21504
	ds_read_b128 v[216:219], v166 offset:22528
	ds_read_b128 v[220:223], v166 offset:23552
	global_load_lds_dwordx4 v[162:163], off
	s_add_i32 m0, s85, 0x2000
	s_add_u32 s88, s24, 0x40000
	v_lshl_add_u64 v[224:225], s[24:25], 0, v[138:139]
	s_addc_u32 s89, s25, 0
	s_add_i32 s85, s90, s28
	global_load_lds_dwordx4 v[224:225], off
	v_lshl_add_u64 v[226:227], s[88:89], 0, v[142:143]
	s_mov_b32 m0, s85
	v_lshl_add_u64 v[228:229], s[26:27], 0, v[140:141]
	global_load_lds_dwordx4 v[226:227], off
	v_lshl_add_u64 v[226:227], s[88:89], 0, v[138:139]
	s_add_i32 m0, s85, 0x2000
	s_nop 0
	global_load_lds_dwordx4 v[226:227], off
	v_lshl_add_u64 v[226:227], s[26:27], 0, v[144:145]
	s_mov_b32 m0, s40
	s_nop 0
	global_load_lds_dwordx4 v[226:227], off
	s_mov_b32 m0, s41
	s_nop 0
	global_load_lds_dwordx4 v[228:229], off
	s_waitcnt vmcnt(8) lgkmcnt(0)
	s_setprio 1
	s_barrier
; #define PG8_STAGE(bufoff, gbase, voff) do { _Pragma("unroll") for (int _i = 0; _i < 2; ++_i) \
;         __builtin_amdgcn_global_load_lds((const unsigned*)((const char*)(gbase) + (voff)[_i]), (LAS unsigned*)(lds + (bufoff) + ldsw + _i * 8192), 16, 0, 0); } while (0)
; #define PG8_LDA(dst, b, h) do { _Pragma("unroll") for (int m = 0; m < 4; ++m) _Pragma("unroll") for (int k = 0; k < 2; ++k) dst[m][k] = *(const LAS bf16x8*)(lds + PG8_SA(b, h) + aoff + m * 2048 + k * 1024); } while (0)
; #define PG8_LDB(dst, b, h) do { _Pragma("unroll") for (int n = 0; n < 2; ++n) _Pragma("unroll") for (int k = 0; k < 2; ++k) dst[n][k] = *(const LAS bf16x8*)(lds + PG8_SB(b, h) + boff + n * 2048 + k * 1024); } while (0)
; #define PG8_MMA(ai, bj, At, Bt) do { __builtin_amdgcn_s_setprio(1); _Pragma("unroll") for (int m = 0; m < 4; ++m) _Pragma("unroll") for (int n = 0; n < 2; ++n) _Pragma("unroll") for (int k = 0; k < 2; ++k) \
;         acc[ai][bj][m][n] = __builtin_amdgcn_mfma_f32_16x16x32_bf16(Bt[n][k], At[m][k], acc[ai][bj][m][n], 0, 0, 0); __builtin_amdgcn_s_setprio(0); } while (0)
; #define PG8_WAIT_V(n) asm volatile("s_waitcnt vmcnt(" #n ")" ::: "memory")
; #define PG8_WAIT_L(n) asm volatile("s_waitcnt lgkmcnt(" #n ")" ::: "memory")
; #define PG8_BAR __builtin_amdgcn_s_barrier()
; #define PG8_SCHED __builtin_amdgcn_sched_barrier(0)
; template <class Epi, class Sched>
; __device__ __forceinline__ void gemm_phase(LAS unsigned char* lds, const Gemm g, const Sched S, const Epi E, const int tid) {
;     ...
;             PG8_WAIT_V(8); PG8_WAIT_L(0); PG8_BAR; PG8_MMA(1, 0, At, B0); PG8_MMA(1, 1, At, B1); PG8_BAR; PG8_SCHED;
;             PG8_LDB(B0, 1, 0); PG8_LDB(B1, 1, 1); PG8_SCHED; PG8_LDA(At, 1, 0); PG8_STAGE(PG8_SA(0, 1), a2 + hstepA, voffA);
;             PG8_WAIT_V(8); PG8_WAIT_L(0); PG8_BAR; PG8_MMA(0, 0, At, B0); PG8_MMA(0, 1, At, B1); PG8_BAR; PG8_SCHED;
	v_mfma_f32_16x16x32_bf16 v[62:65], v[98:101], v[192:195], v[62:65]
	v_mfma_f32_16x16x32_bf16 v[50:53], v[150:153], v[192:195], v[50:53]
	v_mfma_f32_16x16x32_bf16 v[46:49], v[98:101], v[200:203], v[46:49]
	v_mfma_f32_16x16x32_bf16 v[34:37], v[150:153], v[200:203], v[34:37]
	v_mfma_f32_16x16x32_bf16 v[30:33], v[98:101], v[208:211], v[30:33]
	v_mfma_f32_16x16x32_bf16 v[18:21], v[150:153], v[208:211], v[18:21]
	v_mfma_f32_16x16x32_bf16 v[14:17], v[98:101], v[216:219], v[14:17]
	v_mfma_f32_16x16x32_bf16 v[6:9], v[150:153], v[216:219], v[6:9]
	v_mfma_f32_16x16x32_bf16 v[62:65], v[134:137], v[196:199], v[62:65]
	v_mfma_f32_16x16x32_bf16 v[50:53], v[154:157], v[196:199], v[50:53]
	v_mfma_f32_16x16x32_bf16 v[46:49], v[134:137], v[204:207], v[46:49]
	v_mfma_f32_16x16x32_bf16 v[34:37], v[154:157], v[204:207], v[34:37]
	v_mfma_f32_16x16x32_bf16 v[30:33], v[134:137], v[212:215], v[30:33]
	v_mfma_f32_16x16x32_bf16 v[18:21], v[154:157], v[212:215], v[18:21]
	v_mfma_f32_16x16x32_bf16 v[14:17], v[134:137], v[220:223], v[14:17]
	v_mfma_f32_16x16x32_bf16 v[6:9], v[154:157], v[220:223], v[6:9]
	v_mfma_f32_16x16x32_bf16 v[58:61], v[158:161], v[192:195], v[58:61]
	v_mfma_f32_16x16x32_bf16 v[54:57], v[184:187], v[192:195], v[54:57]
	v_mfma_f32_16x16x32_bf16 v[42:45], v[158:161], v[200:203], v[42:45]
	v_mfma_f32_16x16x32_bf16 v[38:41], v[184:187], v[200:203], v[38:41]
	v_mfma_f32_16x16x32_bf16 v[26:29], v[158:161], v[208:211], v[26:29]
	v_mfma_f32_16x16x32_bf16 v[22:25], v[184:187], v[208:211], v[22:25]
	v_mfma_f32_16x16x32_bf16 v[10:13], v[158:161], v[216:219], v[10:13]
	v_mfma_f32_16x16x32_bf16 v[2:5], v[184:187], v[216:219], v[2:5]
	v_mfma_f32_16x16x32_bf16 v[58:61], v[180:183], v[196:199], v[58:61]
	v_mfma_f32_16x16x32_bf16 v[54:57], v[188:191], v[196:199], v[54:57]
	v_mfma_f32_16x16x32_bf16 v[42:45], v[180:183], v[204:207], v[42:45]
	v_mfma_f32_16x16x32_bf16 v[38:41], v[188:191], v[204:207], v[38:41]
	v_mfma_f32_16x16x32_bf16 v[26:29], v[180:183], v[212:215], v[26:29]
	v_mfma_f32_16x16x32_bf16 v[22:25], v[188:191], v[212:215], v[22:25]
	v_mfma_f32_16x16x32_bf16 v[10:13], v[180:183], v[220:223], v[10:13]
	v_mfma_f32_16x16x32_bf16 v[2:5], v[188:191], v[220:223], v[2:5]
	s_barrier
	s_setprio 0
	s_add_i32 s85, 0, 0x18000
	s_add_i32 s88, 0, 0x1c000
	v_add_u32_e32 v154, s85, v165
	v_add_u32_e32 v167, s88, v165
	ds_read_b128 v[98:101], v154
	ds_read_b128 v[134:137], v154 offset:1024
	ds_read_b128 v[150:153], v154 offset:2048
	ds_read_b128 v[154:157], v154 offset:3072
	ds_read_b128 v[158:161], v167
	ds_read_b128 v[180:183], v167 offset:1024
	ds_read_b128 v[184:187], v167 offset:2048
	ds_read_b128 v[188:191], v167 offset:3072
	s_add_u32 s26, s26, 0x40000
	s_addc_u32 s27, s27, 0
	s_mov_b32 m0, s42
	v_lshl_add_u64 v[230:231], s[26:27], 0, v[144:145]
	ds_read_b128 v[192:195], v166 offset:32768
	ds_read_b128 v[196:199], v166 offset:33792
	ds_read_b128 v[200:203], v166 offset:34816
	ds_read_b128 v[204:207], v166 offset:35840
	ds_read_b128 v[208:211], v166 offset:36864
	ds_read_b128 v[212:215], v166 offset:37888
	ds_read_b128 v[216:219], v166 offset:38912
	ds_read_b128 v[220:223], v166 offset:39936
	global_load_lds_dwordx4 v[230:231], off
	v_lshl_add_u64 v[230:231], s[26:27], 0, v[140:141]
	s_mov_b32 m0, s43
	s_nop 0
	global_load_lds_dwordx4 v[230:231], off
	s_waitcnt vmcnt(8) lgkmcnt(0)
	s_setprio 1
	s_barrier
	v_mfma_f32_16x16x32_bf16 v[130:133], v[98:101], v[192:195], v[130:133]
	v_mfma_f32_16x16x32_bf16 v[118:121], v[150:153], v[192:195], v[118:121]
	v_mfma_f32_16x16x32_bf16 v[114:117], v[98:101], v[200:203], v[114:117]
	v_mfma_f32_16x16x32_bf16 v[102:105], v[150:153], v[200:203], v[102:105]
	v_mfma_f32_16x16x32_bf16 v[94:97], v[98:101], v[208:211], v[94:97]
	v_mfma_f32_16x16x32_bf16 v[82:85], v[150:153], v[208:211], v[82:85]
	v_mfma_f32_16x16x32_bf16 v[78:81], v[98:101], v[216:219], v[78:81]
	v_mfma_f32_16x16x32_bf16 v[66:69], v[150:153], v[216:219], v[66:69]
	v_mfma_f32_16x16x32_bf16 v[130:133], v[134:137], v[196:199], v[130:133]
	v_mfma_f32_16x16x32_bf16 v[118:121], v[154:157], v[196:199], v[118:121]
	v_mfma_f32_16x16x32_bf16 v[114:117], v[134:137], v[204:207], v[114:117]
	v_mfma_f32_16x16x32_bf16 v[102:105], v[154:157], v[204:207], v[102:105]
	v_mfma_f32_16x16x32_bf16 v[94:97], v[134:137], v[212:215], v[94:97]
	v_mfma_f32_16x16x32_bf16 v[82:85], v[154:157], v[212:215], v[82:85]
	v_mfma_f32_16x16x32_bf16 v[78:81], v[134:137], v[220:223], v[78:81]
	v_mfma_f32_16x16x32_bf16 v[66:69], v[154:157], v[220:223], v[66:69]
	v_mfma_f32_16x16x32_bf16 v[126:129], v[158:161], v[192:195], v[126:129]
	v_mfma_f32_16x16x32_bf16 v[122:125], v[184:187], v[192:195], v[122:125]
	v_mfma_f32_16x16x32_bf16 v[110:113], v[158:161], v[200:203], v[110:113]
	v_mfma_f32_16x16x32_bf16 v[106:109], v[184:187], v[200:203], v[106:109]
	v_mfma_f32_16x16x32_bf16 v[90:93], v[158:161], v[208:211], v[90:93]
	v_mfma_f32_16x16x32_bf16 v[86:89], v[184:187], v[208:211], v[86:89]
	v_mfma_f32_16x16x32_bf16 v[74:77], v[158:161], v[216:219], v[74:77]
	v_mfma_f32_16x16x32_bf16 v[70:73], v[184:187], v[216:219], v[70:73]
	v_mfma_f32_16x16x32_bf16 v[126:129], v[180:183], v[196:199], v[126:129]
	v_mfma_f32_16x16x32_bf16 v[122:125], v[188:191], v[196:199], v[122:125]
	v_mfma_f32_16x16x32_bf16 v[110:113], v[180:183], v[204:207], v[110:113]
	v_mfma_f32_16x16x32_bf16 v[106:109], v[188:191], v[204:207], v[106:109]
	v_mfma_f32_16x16x32_bf16 v[90:93], v[180:183], v[212:215], v[90:93]
	v_mfma_f32_16x16x32_bf16 v[86:89], v[188:191], v[212:215], v[86:89]
	v_mfma_f32_16x16x32_bf16 v[74:77], v[180:183], v[220:223], v[74:77]
	v_mfma_f32_16x16x32_bf16 v[70:73], v[188:191], v[220:223], v[70:73]
	s_barrier
; #define PG8_STAGE(bufoff, gbase, voff) do { _Pragma("unroll") for (int _i = 0; _i < 2; ++_i) \
;         __builtin_amdgcn_global_load_lds((const unsigned*)((const char*)(gbase) + (voff)[_i]), (LAS unsigned*)(lds + (bufoff) + ldsw + _i * 8192), 16, 0, 0); } while (0)
; #define PG8_LDA(dst, b, h) do { _Pragma("unroll") for (int m = 0; m < 4; ++m) _Pragma("unroll") for (int k = 0; k < 2; ++k) dst[m][k] = *(const LAS bf16x8*)(lds + PG8_SA(b, h) + aoff + m * 2048 + k * 1024); } while (0)
; #define PG8_MMA(ai, bj, At, Bt) do { __builtin_amdgcn_s_setprio(1); _Pragma("unroll") for (int m = 0; m < 4; ++m) _Pragma("unroll") for (int n = 0; n < 2; ++n) _Pragma("unroll") for (int k = 0; k < 2; ++k) \
;         acc[ai][bj][m][n] = __builtin_amdgcn_mfma_f32_16x16x32_bf16(Bt[n][k], At[m][k], acc[ai][bj][m][n], 0, 0, 0); __builtin_amdgcn_s_setprio(0); } while (0)
; #define PG8_WAIT_V(n) asm volatile("s_waitcnt vmcnt(" #n ")" ::: "memory")
; #define PG8_WAIT_L(n) asm volatile("s_waitcnt lgkmcnt(" #n ")" ::: "memory")
; #define PG8_BAR __builtin_amdgcn_s_barrier()
; #define PG8_SCHED __builtin_amdgcn_sched_barrier(0)
; template <class Epi, class Sched>
; __device__ __forceinline__ void gemm_phase(LAS unsigned char* lds, const Gemm g, const Sched S, const Epi E, const int tid) {
;     ...
;             PG8_LDA(At, 1, 1); PG8_STAGE(PG8_SB(1, 0), b3, voffB); PG8_STAGE(PG8_SB(1, 1), b3 + hstepB, voffB); PG8_STAGE(PG8_SA(1, 0), a3, voffA);
;             PG8_WAIT_V(8); PG8_WAIT_L(0); PG8_BAR; PG8_MMA(1, 0, At, B0); PG8_MMA(1, 1, At, B1); PG8_BAR; PG8_SCHED;
;         }
;         if (wr == 0) PG8_BAR;
	s_setprio 0
	s_add_i32 s26, s85, s28
	v_lshl_add_u64 v[162:163], v[162:163], 0, s[64:65]
	s_mov_b32 m0, s26
	ds_read_b128 v[192:195], v166 offset:49152
	ds_read_b128 v[196:199], v166 offset:50176
	ds_read_b128 v[200:203], v166 offset:51200
	ds_read_b128 v[204:207], v166 offset:52224
	ds_read_b128 v[208:211], v166 offset:53248
	ds_read_b128 v[212:215], v166 offset:54272
	ds_read_b128 v[216:219], v166 offset:55296
	ds_read_b128 v[220:223], v166 offset:56320
	global_load_lds_dwordx4 v[162:163], off
	s_add_i32 m0, s26, 0x2000
	s_add_u32 s24, s24, 0x40080
	v_lshl_add_u64 v[162:163], v[224:225], 0, s[64:65]
	s_addc_u32 s25, s25, 0
	s_add_i32 s26, s88, s28
	global_load_lds_dwordx4 v[162:163], off
	v_lshl_add_u64 v[162:163], s[24:25], 0, v[142:143]
	s_mov_b32 m0, s26
	s_nop 0
	global_load_lds_dwordx4 v[162:163], off
	v_lshl_add_u64 v[162:163], s[24:25], 0, v[138:139]
	s_add_i32 m0, s26, 0x2000
	s_nop 0
	global_load_lds_dwordx4 v[162:163], off
	v_lshl_add_u64 v[162:163], v[226:227], 0, s[64:65]
	s_mov_b32 m0, s46
	s_nop 0
	global_load_lds_dwordx4 v[162:163], off
	v_lshl_add_u64 v[162:163], v[228:229], 0, s[64:65]
	s_mov_b32 m0, s47
	s_nop 0
	global_load_lds_dwordx4 v[162:163], off
	s_waitcnt vmcnt(8) lgkmcnt(0)
	s_setprio 1
	s_barrier
	v_mfma_f32_16x16x32_bf16 v[62:65], v[98:101], v[192:195], v[62:65]
	v_mfma_f32_16x16x32_bf16 v[50:53], v[150:153], v[192:195], v[50:53]
	v_mfma_f32_16x16x32_bf16 v[46:49], v[98:101], v[200:203], v[46:49]
	v_mfma_f32_16x16x32_bf16 v[34:37], v[150:153], v[200:203], v[34:37]
	v_mfma_f32_16x16x32_bf16 v[30:33], v[98:101], v[208:211], v[30:33]
	v_mfma_f32_16x16x32_bf16 v[18:21], v[150:153], v[208:211], v[18:21]
	v_mfma_f32_16x16x32_bf16 v[14:17], v[98:101], v[216:219], v[14:17]
	v_mfma_f32_16x16x32_bf16 v[6:9], v[150:153], v[216:219], v[6:9]
	v_mfma_f32_16x16x32_bf16 v[62:65], v[134:137], v[196:199], v[62:65]
	v_mfma_f32_16x16x32_bf16 v[50:53], v[154:157], v[196:199], v[50:53]
	v_mfma_f32_16x16x32_bf16 v[46:49], v[134:137], v[204:207], v[46:49]
	v_mfma_f32_16x16x32_bf16 v[34:37], v[154:157], v[204:207], v[34:37]
	v_mfma_f32_16x16x32_bf16 v[30:33], v[134:137], v[212:215], v[30:33]
	v_mfma_f32_16x16x32_bf16 v[18:21], v[154:157], v[212:215], v[18:21]
	v_mfma_f32_16x16x32_bf16 v[14:17], v[134:137], v[220:223], v[14:17]
	v_mfma_f32_16x16x32_bf16 v[6:9], v[154:157], v[220:223], v[6:9]
	v_mfma_f32_16x16x32_bf16 v[58:61], v[158:161], v[192:195], v[58:61]
	v_mfma_f32_16x16x32_bf16 v[54:57], v[184:187], v[192:195], v[54:57]
	v_mfma_f32_16x16x32_bf16 v[42:45], v[158:161], v[200:203], v[42:45]
	v_mfma_f32_16x16x32_bf16 v[38:41], v[184:187], v[200:203], v[38:41]
	v_mfma_f32_16x16x32_bf16 v[26:29], v[158:161], v[208:211], v[26:29]
	v_mfma_f32_16x16x32_bf16 v[22:25], v[184:187], v[208:211], v[22:25]
	v_mfma_f32_16x16x32_bf16 v[10:13], v[158:161], v[216:219], v[10:13]
	v_mfma_f32_16x16x32_bf16 v[2:5], v[184:187], v[216:219], v[2:5]
	v_mfma_f32_16x16x32_bf16 v[58:61], v[180:183], v[196:199], v[58:61]
	v_mfma_f32_16x16x32_bf16 v[54:57], v[188:191], v[196:199], v[54:57]
	v_mfma_f32_16x16x32_bf16 v[42:45], v[180:183], v[204:207], v[42:45]
	v_mfma_f32_16x16x32_bf16 v[38:41], v[188:191], v[204:207], v[38:41]
	v_mfma_f32_16x16x32_bf16 v[26:29], v[180:183], v[212:215], v[26:29]
	v_mfma_f32_16x16x32_bf16 v[22:25], v[188:191], v[212:215], v[22:25]
	v_mfma_f32_16x16x32_bf16 v[10:13], v[180:183], v[220:223], v[10:13]
	v_mfma_f32_16x16x32_bf16 v[2:5], v[188:191], v[220:223], v[2:5]
	s_barrier
	s_setprio 0
	s_add_i32 s84, s84, 2
	s_add_u32 s82, s82, 0x100
	s_addc_u32 s83, s83, 0
	s_add_u32 s22, s22, 0x100
	s_addc_u32 s23, s23, 0
	s_cmp_gt_u32 s84, 13
	s_cbranch_scc0 .LBB0_819
	s_and_b64 vcc, exec, s[12:13]
	s_cbranch_vccz .LBB0_822
	s_barrier
